# BAR steps: V-fragment ds_reads (slot arithmetic redone in vcc_lo) issued before the step's two global tile loads
# speedup vs baseline: 1.0052x; 1.0052x over previous
.LBB0_641:
	s_mul_i32 vcc_lo, s25, 0x2400
	s_add_i32 vcc_lo, vcc_lo, 0xffffdc00
	s_cmp_lg_u32 s25, 0
	s_cselect_b32 vcc_lo, vcc_lo, 0x9000
	v_add_u32_e32 v1, vcc_lo, v163
	ds_read_b128 v[60:63], v1 offset:36864
	ds_read_b128 v[114:117], v1 offset:36896
	ds_read_b128 v[118:121], v1 offset:41472
	ds_read_b128 v[134:137], v1 offset:41504
	ds_read_b128 v[146:149], v1 offset:36928
	ds_read_b128 v[150:153], v1 offset:36960
	ds_read_b128 v[196:199], v1 offset:41536
	ds_read_b128 v[200:203], v1 offset:41568
	s_add_i32 s24, s23, -7
	s_lshl_b32 s92, s24, 13
	s_add_u32 vcc_lo, s100, s92
	s_addc_u32 vcc_hi, s101, 0
	global_load_dwordx4 v[52:55], v248, vcc
	s_add_i32 s24, s23, -8
	s_lshl_b32 s92, s24, 7
	s_add_u32 vcc_lo, s98, s92
	s_addc_u32 vcc_hi, s99, 0
	global_load_dwordx4 v[56:59], v249, vcc
	s_mul_i32 s26, s25, 0x2400
	s_add_i32 s24, s23, -7
	s_setprio 3
	v_cvt_pk_bf16_f32 v204, v102, v103
	v_cvt_pk_bf16_f32 v205, v104, v105
	v_cvt_pk_bf16_f32 v206, v98, v99
	v_cvt_pk_bf16_f32 v207, v100, v101
	s_waitcnt lgkmcnt(7)
	s_nop 0
	v_mfma_f32_32x32x16_bf16 v[18:33], v[60:63], v[204:207], v[18:33]
	v_add_f32_e32 v1, v102, v103
	v_add_f32_e32 v1, v1, v104
	v_add_f32_e32 v1, v1, v105
	s_waitcnt lgkmcnt(5)
	v_mfma_f32_32x32x16_bf16 v[2:17], v[118:121], v[204:207], v[2:17]
	v_cvt_pk_bf16_f32 v60, v194, v187
	v_cvt_pk_bf16_f32 v61, v186, v185
	v_cvt_pk_bf16_f32 v62, v133, v132
	v_cvt_pk_bf16_f32 v63, v131, v130
	v_add_f32_e32 v1, v1, v98
	v_add_f32_e32 v1, v1, v99
	v_add_f32_e32 v1, v1, v100
	v_add_f32_e32 v1, v1, v101
	s_nop 0
	v_mfma_f32_32x32x16_bf16 v[18:33], v[114:117], v[60:63], v[18:33]
	v_add_f32_e32 v1, v1, v194
	v_add_f32_e32 v1, v1, v187
	v_add_f32_e32 v1, v1, v186
	v_add_f32_e32 v1, v1, v185
	s_waitcnt lgkmcnt(4)
	v_mfma_f32_32x32x16_bf16 v[2:17], v[134:137], v[60:63], v[2:17]
	v_cvt_pk_bf16_f32 v98, v129, v128
	v_cvt_pk_bf16_f32 v99, v127, v126
	v_cvt_pk_bf16_f32 v100, v125, v124
	v_cvt_pk_bf16_f32 v101, v123, v122
	v_add_f32_e32 v1, v1, v133
	v_add_f32_e32 v1, v1, v132
	v_add_f32_e32 v1, v1, v131
	v_add_f32_e32 v1, v1, v130
	s_waitcnt lgkmcnt(3)
	v_mfma_f32_32x32x16_bf16 v[18:33], v[146:149], v[98:101], v[18:33]
	v_add_f32_e32 v1, v1, v129
	v_add_f32_e32 v1, v1, v128
	v_add_f32_e32 v1, v1, v127
	v_add_f32_e32 v1, v1, v126
	s_waitcnt lgkmcnt(1)
	v_mfma_f32_32x32x16_bf16 v[2:17], v[196:199], v[98:101], v[2:17]
	v_cvt_pk_bf16_f32 v60, v109, v108
	v_cvt_pk_bf16_f32 v61, v107, v106
	v_cvt_pk_bf16_f32 v62, v113, v112
	v_cvt_pk_bf16_f32 v63, v111, v110
	v_add_f32_e32 v1, v1, v125
	v_add_f32_e32 v1, v1, v124
	v_add_f32_e32 v1, v1, v123
	v_add_f32_e32 v1, v1, v122
	s_nop 0
	v_mfma_f32_32x32x16_bf16 v[18:33], v[150:153], v[60:63], v[18:33]
	v_add_f32_e32 v1, v1, v109
	v_add_f32_e32 v1, v1, v108
	v_add_f32_e32 v1, v1, v107
	v_add_f32_e32 v1, v1, v106
	s_waitcnt lgkmcnt(0)
	v_mfma_f32_32x32x16_bf16 v[2:17], v[200:203], v[60:63], v[2:17]
	v_add_f32_e32 v1, v1, v113
	v_add_f32_e32 v1, v1, v112
	v_add_f32_e32 v1, v1, v111
	v_add_f32_e32 v1, v1, v110
	s_setprio 2
	s_waitcnt lgkmcnt(0)
	s_barrier
	ds_read_b128 v[240:243], v165 offset:18432
	ds_read_b128 v[244:247], v165 offset:23040
	ds_read_b128 v[130:133], v165 offset:18464
	ds_read_b128 v[146:149], v165 offset:23072
	v_exp_f32_e32 v185, v82
	v_exp_f32_e32 v186, v83
	v_exp_f32_e32 v187, v84
	v_exp_f32_e32 v194, v85
	v_exp_f32_e32 v195, v86
	v_exp_f32_e32 v196, v87
	v_exp_f32_e32 v197, v88
	v_exp_f32_e32 v198, v89
	s_waitcnt lgkmcnt(2)
	v_mfma_f32_32x32x16_bf16 v[114:129], v[240:243], v[158:161], v[34:49]
	s_waitcnt lgkmcnt(1)
	v_mfma_f32_32x32x16_bf16 v[98:113], v[244:247], v[158:161], v[34:49]
	v_exp_f32_e32 v199, v90
	v_exp_f32_e32 v200, v91
	v_exp_f32_e32 v201, v92
	v_exp_f32_e32 v202, v93
	v_exp_f32_e32 v134, v94
	v_exp_f32_e32 v135, v95
	v_exp_f32_e32 v136, v96
	v_exp_f32_e32 v137, v97
	v_mfma_f32_32x32x16_bf16 v[114:129], v[130:133], v[154:157], v[114:129]
	v_exp_f32_e32 v96, v66
	v_exp_f32_e32 v97, v67
	v_exp_f32_e32 v203, v68
	v_exp_f32_e32 v204, v69
	v_exp_f32_e32 v130, v70
	v_exp_f32_e32 v131, v71
	v_exp_f32_e32 v132, v72
	v_exp_f32_e32 v133, v73
	s_waitcnt lgkmcnt(0)
	v_mfma_f32_32x32x16_bf16 v[98:113], v[146:149], v[154:157], v[98:113]
	v_exp_f32_e32 v205, v74
	v_exp_f32_e32 v206, v75
	v_exp_f32_e32 v207, v76
	v_exp_f32_e32 v208, v77
	v_exp_f32_e32 v209, v78
	v_exp_f32_e32 v210, v79
	v_exp_f32_e32 v211, v80
	v_exp_f32_e32 v212, v81
	v_add_u32_e32 v88, s26, v163
	ds_read_b128 v[240:243], v165 offset:27648
	ds_read_b128 v[244:247], v165 offset:32256
	ds_read_b128 v[60:63], v88 offset:41472
	ds_read_b128 v[64:67], v88 offset:36864
	ds_read_b128 v[68:71], v88 offset:36896
	ds_read_b128 v[72:75], v88 offset:41504
	ds_read_b128 v[76:79], v88 offset:36928
	ds_read_b128 v[80:83], v88 offset:41536
	ds_read_b128 v[84:87], v88 offset:36960
	ds_read_b128 v[88:91], v88 offset:41568
	s_cmp_gt_i32 s25, 2
	s_cselect_b32 s27, -3, 2
	s_add_i32 s27, s27, s25
	s_add_i32 s26, s23, -6
	s_mulk_i32 s27, 0x2400
	s_min_u32 s26, s26, s13
	v_add_u32_e32 v51, s27, v182
	s_min_u32 s24, s24, s13
	s_lshl_b32 s92, s26, 13
	s_waitcnt vmcnt(3)
	ds_write_b128 v182, v[138:141]
	s_waitcnt vmcnt(2)
	ds_write_b128 v51, v[142:145] offset:36864
	v_add_f32_e32 v1, v50, v1
	s_add_u32 vcc_lo, s100, s92
	s_addc_u32 vcc_hi, s101, 0
	global_load_dwordx4 v[146:149], v248, vcc
	s_lshl_b32 s92, s24, 7
	s_add_u32 vcc_lo, s98, s92
	s_addc_u32 vcc_hi, s99, 0
	global_load_dwordx4 v[150:153], v249, vcc
	s_add_i32 s27, s25, 1
	s_setprio 1
	v_cvt_pk_bf16_f32 v92, v185, v186
	v_cvt_pk_bf16_f32 v93, v187, v194
	v_cvt_pk_bf16_f32 v94, v195, v196
	v_cvt_pk_bf16_f32 v95, v197, v198
	s_waitcnt lgkmcnt(8)
	s_nop 0
	v_mfma_f32_32x32x16_bf16 v[18:33], v[64:67], v[92:95], v[18:33]
	v_add_f32_e32 v213, v185, v186
	v_add_f32_e32 v213, v213, v187
	v_add_f32_e32 v213, v213, v194
	s_nop 0
	v_mfma_f32_32x32x16_bf16 v[2:17], v[60:63], v[92:95], v[2:17]
	v_cvt_pk_bf16_f32 v64, v199, v200
	v_cvt_pk_bf16_f32 v65, v201, v202
	v_cvt_pk_bf16_f32 v66, v134, v135
	v_cvt_pk_bf16_f32 v67, v136, v137
	v_add_f32_e32 v213, v213, v195
	v_add_f32_e32 v213, v213, v196
	v_add_f32_e32 v213, v213, v197
	v_add_f32_e32 v213, v213, v198
	s_waitcnt lgkmcnt(7)
	v_mfma_f32_32x32x16_bf16 v[18:33], v[68:71], v[64:67], v[18:33]
	v_add_f32_e32 v213, v213, v199
	v_add_f32_e32 v213, v213, v200
	v_add_f32_e32 v213, v213, v201
	v_add_f32_e32 v213, v213, v202
	s_waitcnt lgkmcnt(6)
	v_mfma_f32_32x32x16_bf16 v[2:17], v[72:75], v[64:67], v[2:17]
	v_cvt_pk_bf16_f32 v60, v96, v97
	v_cvt_pk_bf16_f32 v61, v203, v204
	v_cvt_pk_bf16_f32 v62, v130, v131
	v_cvt_pk_bf16_f32 v63, v132, v133
	v_add_f32_e32 v213, v213, v134
	v_add_f32_e32 v213, v213, v135
	v_add_f32_e32 v213, v213, v136
	v_add_f32_e32 v213, v213, v137
	s_waitcnt lgkmcnt(5)
	v_mfma_f32_32x32x16_bf16 v[18:33], v[76:79], v[60:63], v[18:33]
	v_add_f32_e32 v213, v213, v96
	v_add_f32_e32 v213, v213, v97
	v_add_f32_e32 v213, v213, v203
	v_add_f32_e32 v213, v213, v204
	s_waitcnt lgkmcnt(4)
	v_mfma_f32_32x32x16_bf16 v[2:17], v[80:83], v[60:63], v[2:17]
	v_cvt_pk_bf16_f32 v64, v205, v206
	v_cvt_pk_bf16_f32 v65, v207, v208
	v_cvt_pk_bf16_f32 v66, v209, v210
	v_cvt_pk_bf16_f32 v67, v211, v212
	v_add_f32_e32 v213, v213, v130
	v_add_f32_e32 v213, v213, v131
	v_add_f32_e32 v213, v213, v132
	v_add_f32_e32 v213, v213, v133
	s_waitcnt lgkmcnt(3)
	v_mfma_f32_32x32x16_bf16 v[18:33], v[84:87], v[64:67], v[18:33]
	v_add_f32_e32 v213, v213, v205
	v_add_f32_e32 v213, v213, v206
	v_add_f32_e32 v213, v213, v207
	v_add_f32_e32 v213, v213, v208
	s_waitcnt lgkmcnt(2)
	v_mfma_f32_32x32x16_bf16 v[2:17], v[88:91], v[64:67], v[2:17]
	v_add_f32_e32 v213, v213, v209
	v_add_f32_e32 v213, v213, v210
	v_add_f32_e32 v213, v213, v211
	v_add_f32_e32 v213, v213, v212
	s_setprio 0
	ds_read_b128 v[64:67], v165 offset:27680
	ds_read_b128 v[72:75], v165 offset:32288
	s_cmp_lg_u32 s25, 4
	s_cselect_b32 s24, s27, 0
	s_waitcnt lgkmcnt(2)
	v_mfma_f32_32x32x16_bf16 v[130:145], v[240:243], v[158:161], v[34:49]
	v_exp_f32_e32 v185, v114
	v_exp_f32_e32 v186, v115
	v_exp_f32_e32 v187, v116
	v_exp_f32_e32 v194, v117
	v_exp_f32_e32 v195, v118
	v_exp_f32_e32 v196, v119
	v_exp_f32_e32 v197, v120
	v_exp_f32_e32 v198, v121
	s_waitcnt lgkmcnt(1)
	v_mfma_f32_32x32x16_bf16 v[82:97], v[244:247], v[158:161], v[34:49]
	v_exp_f32_e32 v199, v122
	v_exp_f32_e32 v200, v123
	v_exp_f32_e32 v201, v124
	v_exp_f32_e32 v202, v125
	v_exp_f32_e32 v122, v126
	v_exp_f32_e32 v123, v127
	v_exp_f32_e32 v124, v128
	v_exp_f32_e32 v125, v129
	v_mfma_f32_32x32x16_bf16 v[130:145], v[64:67], v[154:157], v[130:145]
	v_exp_f32_e32 v126, v98
	v_exp_f32_e32 v127, v99
	v_exp_f32_e32 v128, v100
	v_exp_f32_e32 v129, v101
	v_exp_f32_e32 v203, v102
	v_exp_f32_e32 v204, v103
	v_exp_f32_e32 v205, v104
	v_exp_f32_e32 v206, v105
	s_waitcnt lgkmcnt(0)
	v_mfma_f32_32x32x16_bf16 v[82:97], v[72:75], v[154:157], v[82:97]
	v_exp_f32_e32 v102, v106
	v_exp_f32_e32 v103, v107
	v_exp_f32_e32 v104, v108
	v_exp_f32_e32 v105, v109
	v_exp_f32_e32 v106, v110
	v_exp_f32_e32 v107, v111
	v_exp_f32_e32 v108, v112
	v_exp_f32_e32 v109, v113
	s_cmp_gt_i32 s24, 2
	s_cselect_b32 s25, -3, 2
	s_add_i32 s25, s25, s24
	s_mulk_i32 s25, 0x2400
	v_add_u32_e32 v50, s25, v182
	s_add_i32 s25, s24, 1
	s_cmp_lg_u32 s24, 4
	s_cselect_b32 s24, s25, 0
	s_add_i32 s25, s23, -5
	s_min_u32 s25, s25, s13
	s_lshl_b32 s92, s25, 13
	s_waitcnt vmcnt(3)
	ds_write_b128 v182, v[52:55] offset:9216
	s_waitcnt vmcnt(2)
	ds_write_b128 v50, v[56:59] offset:36864
	s_mul_i32 vcc_lo, s24, 0x2400
	s_add_i32 vcc_lo, vcc_lo, 0xffffdc00
	s_cmp_lg_u32 s24, 0
	s_cselect_b32 vcc_lo, vcc_lo, 0x9000
	v_add_u32_e32 v78, vcc_lo, v163
	ds_read_b128 v[50:53], v78 offset:36864
	ds_read_b128 v[54:57], v78 offset:36896
	ds_read_b128 v[58:61], v78 offset:41472
	ds_read_b128 v[62:65], v78 offset:41504
	ds_read_b128 v[66:69], v78 offset:36928
	ds_read_b128 v[70:73], v78 offset:36960
	ds_read_b128 v[74:77], v78 offset:41536
	ds_read_b128 v[78:81], v78 offset:41568
	s_add_u32 vcc_lo, s100, s92
	s_addc_u32 vcc_hi, s101, 0
	global_load_dwordx4 v[118:121], v248, vcc
	s_lshl_b32 s92, s26, 7
	s_add_u32 vcc_lo, s98, s92
	s_addc_u32 vcc_hi, s99, 0
	global_load_dwordx4 v[114:117], v249, vcc
	s_mul_i32 s26, s24, 0x2400
	s_setprio 3
	v_cvt_pk_bf16_f32 v98, v185, v186
	v_cvt_pk_bf16_f32 v99, v187, v194
	v_cvt_pk_bf16_f32 v100, v195, v196
	v_cvt_pk_bf16_f32 v101, v197, v198
	s_waitcnt lgkmcnt(7)
	s_nop 0
	v_mfma_f32_32x32x16_bf16 v[18:33], v[50:53], v[98:101], v[18:33]
	v_add_f32_e32 v110, v185, v186
	v_add_f32_e32 v110, v110, v187
	v_add_f32_e32 v110, v110, v194
	s_waitcnt lgkmcnt(5)
	v_mfma_f32_32x32x16_bf16 v[2:17], v[58:61], v[98:101], v[2:17]
	v_cvt_pk_bf16_f32 v50, v199, v200
	v_cvt_pk_bf16_f32 v51, v201, v202
	v_cvt_pk_bf16_f32 v52, v122, v123
	v_cvt_pk_bf16_f32 v53, v124, v125
	v_add_f32_e32 v110, v110, v195
	v_add_f32_e32 v110, v110, v196
	v_add_f32_e32 v110, v110, v197
	v_add_f32_e32 v110, v110, v198
	s_nop 0
	v_mfma_f32_32x32x16_bf16 v[18:33], v[54:57], v[50:53], v[18:33]
	v_add_f32_e32 v110, v110, v199
	v_add_f32_e32 v110, v110, v200
	v_add_f32_e32 v110, v110, v201
	v_add_f32_e32 v110, v110, v202
	s_waitcnt lgkmcnt(4)
	v_mfma_f32_32x32x16_bf16 v[2:17], v[62:65], v[50:53], v[2:17]
	v_cvt_pk_bf16_f32 v54, v126, v127
	v_cvt_pk_bf16_f32 v55, v128, v129
	v_cvt_pk_bf16_f32 v56, v203, v204
	v_cvt_pk_bf16_f32 v57, v205, v206
	v_add_f32_e32 v110, v110, v122
	v_add_f32_e32 v110, v110, v123
	v_add_f32_e32 v110, v110, v124
	v_add_f32_e32 v110, v110, v125
	s_waitcnt lgkmcnt(3)
	v_mfma_f32_32x32x16_bf16 v[18:33], v[66:69], v[54:57], v[18:33]
	v_add_f32_e32 v110, v110, v126
	v_add_f32_e32 v110, v110, v127
	v_add_f32_e32 v110, v110, v128
	v_add_f32_e32 v110, v110, v129
	s_waitcnt lgkmcnt(1)
	v_mfma_f32_32x32x16_bf16 v[2:17], v[74:77], v[54:57], v[2:17]
	v_cvt_pk_bf16_f32 v50, v102, v103
	v_cvt_pk_bf16_f32 v51, v104, v105
	v_cvt_pk_bf16_f32 v52, v106, v107
	v_cvt_pk_bf16_f32 v53, v108, v109
	v_add_f32_e32 v110, v110, v203
	v_add_f32_e32 v110, v110, v204
	v_add_f32_e32 v110, v110, v205
	v_add_f32_e32 v110, v110, v206
	s_nop 0
	v_mfma_f32_32x32x16_bf16 v[18:33], v[70:73], v[50:53], v[18:33]
	v_add_f32_e32 v110, v110, v102
	v_add_f32_e32 v110, v110, v103
	v_add_f32_e32 v110, v110, v104
	v_add_f32_e32 v110, v110, v105
	s_waitcnt lgkmcnt(0)
	v_mfma_f32_32x32x16_bf16 v[2:17], v[78:81], v[50:53], v[2:17]
	v_add_f32_e32 v110, v110, v106
	v_add_f32_e32 v110, v110, v107
	v_add_f32_e32 v110, v110, v108
	v_add_f32_e32 v110, v110, v109
	s_setprio 2
	s_waitcnt lgkmcnt(0)
	s_barrier
	ds_read_b128 v[240:243], v165
	ds_read_b128 v[244:247], v165 offset:4608
	ds_read_b128 v[102:105], v165 offset:32
	ds_read_b128 v[106:109], v165 offset:4640
	v_add_f32_e32 v1, v1, v213
	v_exp_f32_e32 v185, v130
	v_exp_f32_e32 v186, v131
	v_exp_f32_e32 v187, v132
	v_exp_f32_e32 v194, v133
	v_exp_f32_e32 v195, v134
	v_exp_f32_e32 v196, v135
	v_exp_f32_e32 v197, v136
	v_exp_f32_e32 v198, v137
	s_waitcnt lgkmcnt(2)
	v_mfma_f32_32x32x16_bf16 v[66:81], v[240:243], v[158:161], v[34:49]
	v_mfma_f32_32x32x16_bf16 v[50:65], v[244:247], v[158:161], v[34:49]
	v_exp_f32_e32 v134, v138
	v_exp_f32_e32 v135, v139
	v_exp_f32_e32 v136, v140
	v_exp_f32_e32 v137, v141
	v_exp_f32_e32 v138, v142
	v_exp_f32_e32 v139, v143
	v_exp_f32_e32 v140, v144
	v_exp_f32_e32 v141, v145
	s_waitcnt lgkmcnt(1)
	v_mfma_f32_32x32x16_bf16 v[66:81], v[102:105], v[154:157], v[66:81]
	v_exp_f32_e32 v142, v82
	v_exp_f32_e32 v143, v83
	v_exp_f32_e32 v144, v84
	v_exp_f32_e32 v145, v85
	v_exp_f32_e32 v199, v86
	v_exp_f32_e32 v200, v87
	v_exp_f32_e32 v201, v88
	v_exp_f32_e32 v202, v89
	s_waitcnt lgkmcnt(0)
	v_mfma_f32_32x32x16_bf16 v[50:65], v[106:109], v[154:157], v[50:65]
	v_exp_f32_e32 v203, v90
	v_exp_f32_e32 v204, v91
	v_exp_f32_e32 v205, v92
	v_exp_f32_e32 v206, v93
	v_exp_f32_e32 v207, v94
	v_exp_f32_e32 v208, v95
	v_exp_f32_e32 v209, v96
	v_exp_f32_e32 v210, v97
	v_add_f32_e32 v1, v1, v110
	v_add_u32_e32 v111, s26, v163
	ds_read_b128 v[240:243], v165 offset:9216
	ds_read_b128 v[244:247], v165 offset:13824
	ds_read_b128 v[82:85], v111 offset:41472
	ds_read_b128 v[86:89], v111 offset:36864
	ds_read_b128 v[90:93], v111 offset:36896
	ds_read_b128 v[94:97], v111 offset:41504
	ds_read_b128 v[98:101], v111 offset:36928
	ds_read_b128 v[102:105], v111 offset:41536
	ds_read_b128 v[106:109], v111 offset:36960
	ds_read_b128 v[110:113], v111 offset:41568
	s_cmp_gt_i32 s24, 2
	s_cselect_b32 s27, -3, 2
	s_add_i32 s27, s27, s24
	s_mulk_i32 s27, 0x2400
	v_add_u32_e32 v250, s27, v182
	s_mov_b32 s27, 0x18950000
	s_waitcnt vmcnt(3)
	ds_write_b128 v182, v[146:149] offset:18432
	s_waitcnt vmcnt(2)
	ds_write_b128 v250, v[150:153] offset:36864
	s_add_i32 s92, s23, -4
	s_lshl_b32 s92, s92, 13
	s_add_u32 vcc_lo, s100, s92
	s_addc_u32 vcc_hi, s101, 0
	global_load_dwordx4 v[126:129], v248, vcc
	s_lshl_b32 s92, s25, 7
	s_add_u32 vcc_lo, s98, s92
	s_addc_u32 vcc_hi, s99, 0
	global_load_dwordx4 v[122:125], v249, vcc
	s_add_i32 s26, s24, 1
	s_setprio 1
	v_cvt_pk_bf16_f32 v130, v185, v186
	v_cvt_pk_bf16_f32 v131, v187, v194
	v_cvt_pk_bf16_f32 v132, v195, v196
	v_cvt_pk_bf16_f32 v133, v197, v198
	s_waitcnt lgkmcnt(8)
	s_nop 0
	v_mfma_f32_32x32x16_bf16 v[18:33], v[86:89], v[130:133], v[18:33]
	v_add_f32_e32 v146, v185, v186
	v_add_f32_e32 v146, v146, v187
	v_add_f32_e32 v146, v146, v194
	s_nop 0
	v_mfma_f32_32x32x16_bf16 v[2:17], v[82:85], v[130:133], v[2:17]
	v_cvt_pk_bf16_f32 v86, v134, v135
	v_cvt_pk_bf16_f32 v87, v136, v137
	v_cvt_pk_bf16_f32 v88, v138, v139
	v_cvt_pk_bf16_f32 v89, v140, v141
	v_add_f32_e32 v146, v146, v195
	v_add_f32_e32 v146, v146, v196
	v_add_f32_e32 v146, v146, v197
	v_add_f32_e32 v146, v146, v198
	s_waitcnt lgkmcnt(7)
	v_mfma_f32_32x32x16_bf16 v[18:33], v[90:93], v[86:89], v[18:33]
	v_add_f32_e32 v146, v146, v134
	v_add_f32_e32 v146, v146, v135
	v_add_f32_e32 v146, v146, v136
	v_add_f32_e32 v146, v146, v137
	s_waitcnt lgkmcnt(6)
	v_mfma_f32_32x32x16_bf16 v[2:17], v[94:97], v[86:89], v[2:17]
	v_cvt_pk_bf16_f32 v82, v142, v143
	v_cvt_pk_bf16_f32 v83, v144, v145
	v_cvt_pk_bf16_f32 v84, v199, v200
	v_cvt_pk_bf16_f32 v85, v201, v202
	v_add_f32_e32 v146, v146, v138
	v_add_f32_e32 v146, v146, v139
	v_add_f32_e32 v146, v146, v140
	v_add_f32_e32 v146, v146, v141
	s_waitcnt lgkmcnt(5)
	v_mfma_f32_32x32x16_bf16 v[18:33], v[98:101], v[82:85], v[18:33]
	v_add_f32_e32 v146, v146, v142
	v_add_f32_e32 v146, v146, v143
	v_add_f32_e32 v146, v146, v144
	v_add_f32_e32 v146, v146, v145
	s_waitcnt lgkmcnt(4)
	v_mfma_f32_32x32x16_bf16 v[2:17], v[102:105], v[82:85], v[2:17]
	v_cvt_pk_bf16_f32 v86, v203, v204
	v_cvt_pk_bf16_f32 v87, v205, v206
	v_cvt_pk_bf16_f32 v88, v207, v208
	v_cvt_pk_bf16_f32 v89, v209, v210
	v_add_f32_e32 v146, v146, v199
	v_add_f32_e32 v146, v146, v200
	v_add_f32_e32 v146, v146, v201
	v_add_f32_e32 v146, v146, v202
	s_waitcnt lgkmcnt(3)
	v_mfma_f32_32x32x16_bf16 v[18:33], v[106:109], v[86:89], v[18:33]
	v_add_f32_e32 v146, v146, v203
	v_add_f32_e32 v146, v146, v204
	v_add_f32_e32 v146, v146, v205
	v_add_f32_e32 v146, v146, v206
	s_waitcnt lgkmcnt(2)
	v_mfma_f32_32x32x16_bf16 v[2:17], v[110:113], v[86:89], v[2:17]
	v_add_f32_e32 v146, v146, v207
	v_add_f32_e32 v146, v146, v208
	v_add_f32_e32 v146, v146, v209
	v_add_f32_e32 v146, v146, v210
	s_setprio 0
	ds_read_b128 v[130:133], v165 offset:9248
	ds_read_b128 v[138:141], v165 offset:13856
	s_cmp_lg_u32 s24, 4
	s_cselect_b32 s24, s26, 0
	s_waitcnt lgkmcnt(2)
	v_mfma_f32_32x32x16_bf16 v[98:113], v[240:243], v[158:161], v[34:49]
	v_exp_f32_e32 v142, v66
	v_exp_f32_e32 v143, v67
	v_exp_f32_e32 v144, v68
	v_exp_f32_e32 v145, v69
	v_exp_f32_e32 v147, v70
	v_exp_f32_e32 v148, v71
	v_exp_f32_e32 v149, v72
	v_exp_f32_e32 v150, v73
	s_waitcnt lgkmcnt(1)
	v_mfma_f32_32x32x16_bf16 v[82:97], v[244:247], v[158:161], v[34:49]
	v_exp_f32_e32 v151, v74
	v_exp_f32_e32 v152, v75
	v_exp_f32_e32 v153, v76
	v_exp_f32_e32 v178, v77
	v_exp_f32_e32 v134, v78
	v_exp_f32_e32 v135, v79
	v_exp_f32_e32 v136, v80
	v_exp_f32_e32 v137, v81
	v_mfma_f32_32x32x16_bf16 v[98:113], v[130:133], v[154:157], v[98:113]
	v_exp_f32_e32 v179, v50
	v_exp_f32_e32 v185, v51
	v_exp_f32_e32 v186, v52
	v_exp_f32_e32 v187, v53
	v_exp_f32_e32 v194, v54
	v_exp_f32_e32 v195, v55
	v_exp_f32_e32 v196, v56
	v_exp_f32_e32 v197, v57
	s_waitcnt lgkmcnt(0)
	v_mfma_f32_32x32x16_bf16 v[82:97], v[138:141], v[154:157], v[82:97]
	v_exp_f32_e32 v198, v58
	v_exp_f32_e32 v199, v59
	v_exp_f32_e32 v200, v60
	v_exp_f32_e32 v201, v61
	v_exp_f32_e32 v138, v62
	v_exp_f32_e32 v139, v63
	v_exp_f32_e32 v140, v64
	v_exp_f32_e32 v141, v65
	s_cmp_gt_i32 s24, 2
	s_cselect_b32 s25, -3, 2
	s_add_i32 s25, s25, s24
	s_mulk_i32 s25, 0x2400
	v_add_u32_e32 v50, s25, v182
	s_add_i32 s25, s24, 1
	s_cmp_lg_u32 s24, 4
	s_cselect_b32 s25, s25, 0
	s_add_i32 s24, s23, -3
	s_min_u32 s26, s24, s13
	s_lshl_b32 s92, s26, 13
	s_waitcnt vmcnt(3)
	ds_write_b128 v182, v[118:121] offset:27648
	s_waitcnt vmcnt(2)
	ds_write_b128 v50, v[114:117] offset:36864
	s_mul_i32 vcc_lo, s25, 0x2400
	s_add_i32 vcc_lo, vcc_lo, 0xffffdc00
	s_cmp_lg_u32 s25, 0
	s_cselect_b32 vcc_lo, vcc_lo, 0x9000
	v_add_u32_e32 v78, vcc_lo, v163
	ds_read_b128 v[50:53], v78 offset:36864
	ds_read_b128 v[54:57], v78 offset:36896
	ds_read_b128 v[58:61], v78 offset:41472
	ds_read_b128 v[62:65], v78 offset:41504
	ds_read_b128 v[66:69], v78 offset:36928
	ds_read_b128 v[70:73], v78 offset:36960
	ds_read_b128 v[74:77], v78 offset:41536
	ds_read_b128 v[78:81], v78 offset:41568
	s_add_u32 vcc_lo, s100, s92
	s_addc_u32 vcc_hi, s101, 0
	global_load_dwordx4 v[118:121], v248, vcc
	s_add_i32 s92, s23, -4
	s_lshl_b32 s92, s92, 7
	s_add_u32 vcc_lo, s98, s92
	s_addc_u32 vcc_hi, s99, 0
	global_load_dwordx4 v[114:117], v249, vcc
	s_mul_i32 s27, s25, 0x2400
	s_setprio 3
	v_cvt_pk_bf16_f32 v130, v142, v143
	v_cvt_pk_bf16_f32 v131, v144, v145
	v_cvt_pk_bf16_f32 v132, v147, v148
	v_cvt_pk_bf16_f32 v133, v149, v150
	s_waitcnt lgkmcnt(7)
	s_nop 0
	v_mfma_f32_32x32x16_bf16 v[18:33], v[50:53], v[130:133], v[18:33]
	v_add_f32_e32 v176, v142, v143
	v_add_f32_e32 v176, v176, v144
	v_add_f32_e32 v176, v176, v145
	s_waitcnt lgkmcnt(5)
	v_mfma_f32_32x32x16_bf16 v[2:17], v[58:61], v[130:133], v[2:17]
	v_cvt_pk_bf16_f32 v50, v151, v152
	v_cvt_pk_bf16_f32 v51, v153, v178
	v_cvt_pk_bf16_f32 v52, v134, v135
	v_cvt_pk_bf16_f32 v53, v136, v137
	v_add_f32_e32 v176, v176, v147
	v_add_f32_e32 v176, v176, v148
	v_add_f32_e32 v176, v176, v149
	v_add_f32_e32 v176, v176, v150
	s_nop 0
	v_mfma_f32_32x32x16_bf16 v[18:33], v[54:57], v[50:53], v[18:33]
	v_add_f32_e32 v176, v176, v151
	v_add_f32_e32 v176, v176, v152
	v_add_f32_e32 v176, v176, v153
	v_add_f32_e32 v176, v176, v178
	s_waitcnt lgkmcnt(4)
	v_mfma_f32_32x32x16_bf16 v[2:17], v[62:65], v[50:53], v[2:17]
	v_cvt_pk_bf16_f32 v54, v179, v185
	v_cvt_pk_bf16_f32 v55, v186, v187
	v_cvt_pk_bf16_f32 v56, v194, v195
	v_cvt_pk_bf16_f32 v57, v196, v197
	v_add_f32_e32 v176, v176, v134
	v_add_f32_e32 v176, v176, v135
	v_add_f32_e32 v176, v176, v136
	v_add_f32_e32 v176, v176, v137
	s_waitcnt lgkmcnt(3)
	v_mfma_f32_32x32x16_bf16 v[18:33], v[66:69], v[54:57], v[18:33]
	v_add_f32_e32 v176, v176, v179
	v_add_f32_e32 v176, v176, v185
	v_add_f32_e32 v176, v176, v186
	v_add_f32_e32 v176, v176, v187
	s_waitcnt lgkmcnt(1)
	v_mfma_f32_32x32x16_bf16 v[2:17], v[74:77], v[54:57], v[2:17]
	v_cvt_pk_bf16_f32 v50, v198, v199
	v_cvt_pk_bf16_f32 v51, v200, v201
	v_cvt_pk_bf16_f32 v52, v138, v139
	v_cvt_pk_bf16_f32 v53, v140, v141
	v_add_f32_e32 v176, v176, v194
	v_add_f32_e32 v176, v176, v195
	v_add_f32_e32 v176, v176, v196
	v_add_f32_e32 v176, v176, v197
	s_nop 0
	v_mfma_f32_32x32x16_bf16 v[18:33], v[70:73], v[50:53], v[18:33]
	v_add_f32_e32 v176, v176, v198
	v_add_f32_e32 v176, v176, v199
	v_add_f32_e32 v176, v176, v200
	v_add_f32_e32 v176, v176, v201
	s_waitcnt lgkmcnt(0)
	v_mfma_f32_32x32x16_bf16 v[2:17], v[78:81], v[50:53], v[2:17]
	v_add_f32_e32 v176, v176, v138
	v_add_f32_e32 v176, v176, v139
	v_add_f32_e32 v176, v176, v140
	v_add_f32_e32 v176, v176, v141
	s_setprio 2
	s_waitcnt lgkmcnt(0)
	s_barrier
	ds_read_b128 v[240:243], v165 offset:18432
	ds_read_b128 v[244:247], v165 offset:23040
	ds_read_b128 v[134:137], v165 offset:18464
	ds_read_b128 v[138:141], v165 offset:23072
	v_add_f32_e32 v1, v1, v146
	v_exp_f32_e32 v142, v98
	v_exp_f32_e32 v143, v99
	v_exp_f32_e32 v144, v100
	v_exp_f32_e32 v145, v101
	v_exp_f32_e32 v146, v102
	v_exp_f32_e32 v147, v103
	v_exp_f32_e32 v148, v104
	v_exp_f32_e32 v149, v105
	s_waitcnt lgkmcnt(2)
	v_mfma_f32_32x32x16_bf16 v[66:81], v[240:243], v[158:161], v[34:49]
	v_mfma_f32_32x32x16_bf16 v[50:65], v[244:247], v[158:161], v[34:49]
	v_exp_f32_e32 v150, v106
	v_exp_f32_e32 v151, v107
	v_exp_f32_e32 v152, v108
	v_exp_f32_e32 v153, v109
	v_exp_f32_e32 v177, v110
	v_exp_f32_e32 v178, v111
	v_exp_f32_e32 v179, v112
	v_exp_f32_e32 v185, v113
	s_waitcnt lgkmcnt(1)
	v_mfma_f32_32x32x16_bf16 v[66:81], v[134:137], v[154:157], v[66:81]
	v_exp_f32_e32 v186, v82
	v_exp_f32_e32 v187, v83
	v_exp_f32_e32 v194, v84
	v_exp_f32_e32 v195, v85
	v_exp_f32_e32 v134, v86
	v_exp_f32_e32 v135, v87
	v_exp_f32_e32 v136, v88
	v_exp_f32_e32 v137, v89
	s_waitcnt lgkmcnt(0)
	v_mfma_f32_32x32x16_bf16 v[50:65], v[138:141], v[154:157], v[50:65]
	v_exp_f32_e32 v196, v90
	v_exp_f32_e32 v197, v91
	v_exp_f32_e32 v198, v92
	v_exp_f32_e32 v199, v93
	v_exp_f32_e32 v138, v94
	v_exp_f32_e32 v139, v95
	v_exp_f32_e32 v140, v96
	v_exp_f32_e32 v141, v97
	s_cmp_gt_i32 s25, 2
	s_cselect_b32 s28, -3, 2
	s_waitcnt vmcnt(3)
	ds_write_b128 v182, v[126:129]
	s_add_i32 s28, s28, s25
	v_add_u32_e32 v126, s27, v163
	s_add_i32 s27, s23, -2
	s_mulk_i32 s28, 0x2400
	s_min_u32 s27, s27, s13
	v_add_u32_e32 v82, s28, v182
	s_lshl_b32 s92, s27, 13
	s_waitcnt vmcnt(2)
	ds_write_b128 v82, v[122:125] offset:36864
	ds_read_b128 v[240:243], v165 offset:27648
	ds_read_b128 v[244:247], v165 offset:32256
	ds_read_b128 v[82:85], v126 offset:41472
	ds_read_b128 v[86:89], v126 offset:36864
	ds_read_b128 v[90:93], v126 offset:36896
	ds_read_b128 v[94:97], v126 offset:41504
	ds_read_b128 v[106:109], v126 offset:36928
	ds_read_b128 v[110:113], v126 offset:41536
	ds_read_b128 v[122:125], v126 offset:36960
	ds_read_b128 v[126:129], v126 offset:41568
	s_add_u32 vcc_lo, s100, s92
	s_addc_u32 vcc_hi, s101, 0
	global_load_dwordx4 v[98:101], v248, vcc
	s_lshl_b32 s92, s26, 7
	s_add_u32 vcc_lo, s98, s92
	s_addc_u32 vcc_hi, s99, 0
	global_load_dwordx4 v[102:105], v249, vcc
	v_add_f32_e32 v1, v1, v176
	s_add_i32 s28, s25, 1
	s_setprio 1
	v_cvt_pk_bf16_f32 v130, v142, v143
	v_cvt_pk_bf16_f32 v131, v144, v145
	v_cvt_pk_bf16_f32 v132, v146, v147
	v_cvt_pk_bf16_f32 v133, v148, v149
	s_waitcnt lgkmcnt(6)
	s_nop 0
	v_mfma_f32_32x32x16_bf16 v[18:33], v[86:89], v[130:133], v[18:33]
	v_add_f32_e32 v176, v142, v143
	v_add_f32_e32 v176, v176, v144
	v_add_f32_e32 v176, v176, v145
	s_nop 0
	v_mfma_f32_32x32x16_bf16 v[2:17], v[82:85], v[130:133], v[2:17]
	v_cvt_pk_bf16_f32 v86, v150, v151
	v_cvt_pk_bf16_f32 v87, v152, v153
	v_cvt_pk_bf16_f32 v88, v177, v178
	v_cvt_pk_bf16_f32 v89, v179, v185
	v_add_f32_e32 v176, v176, v146
	v_add_f32_e32 v176, v176, v147
	v_add_f32_e32 v176, v176, v148
	v_add_f32_e32 v176, v176, v149
	s_waitcnt lgkmcnt(5)
	v_mfma_f32_32x32x16_bf16 v[18:33], v[90:93], v[86:89], v[18:33]
	v_add_f32_e32 v176, v176, v150
	v_add_f32_e32 v176, v176, v151
	v_add_f32_e32 v176, v176, v152
	v_add_f32_e32 v176, v176, v153
	s_waitcnt lgkmcnt(4)
	v_mfma_f32_32x32x16_bf16 v[2:17], v[94:97], v[86:89], v[2:17]
	v_cvt_pk_bf16_f32 v82, v186, v187
	v_cvt_pk_bf16_f32 v83, v194, v195
	v_cvt_pk_bf16_f32 v84, v134, v135
	v_cvt_pk_bf16_f32 v85, v136, v137
	v_add_f32_e32 v176, v176, v177
	v_add_f32_e32 v176, v176, v178
	v_add_f32_e32 v176, v176, v179
	v_add_f32_e32 v176, v176, v185
	s_waitcnt lgkmcnt(3)
	v_mfma_f32_32x32x16_bf16 v[18:33], v[106:109], v[82:85], v[18:33]
	v_add_f32_e32 v176, v176, v186
	v_add_f32_e32 v176, v176, v187
	v_add_f32_e32 v176, v176, v194
	v_add_f32_e32 v176, v176, v195
	s_waitcnt lgkmcnt(2)
	v_mfma_f32_32x32x16_bf16 v[2:17], v[110:113], v[82:85], v[2:17]
	v_cvt_pk_bf16_f32 v86, v196, v197
	v_cvt_pk_bf16_f32 v87, v198, v199
	v_cvt_pk_bf16_f32 v88, v138, v139
	v_cvt_pk_bf16_f32 v89, v140, v141
	v_add_f32_e32 v176, v176, v134
	v_add_f32_e32 v176, v176, v135
	v_add_f32_e32 v176, v176, v136
	v_add_f32_e32 v176, v176, v137
	s_waitcnt lgkmcnt(1)
	v_mfma_f32_32x32x16_bf16 v[18:33], v[122:125], v[86:89], v[18:33]
	v_add_f32_e32 v176, v176, v196
	v_add_f32_e32 v176, v176, v197
	v_add_f32_e32 v176, v176, v198
	v_add_f32_e32 v176, v176, v199
	s_waitcnt lgkmcnt(0)
	v_mfma_f32_32x32x16_bf16 v[2:17], v[126:129], v[86:89], v[2:17]
	v_add_f32_e32 v176, v176, v138
	v_add_f32_e32 v176, v176, v139
	v_add_f32_e32 v176, v176, v140
	v_add_f32_e32 v176, v176, v141
	s_setprio 0
	ds_read_b128 v[106:109], v165 offset:27680
	ds_read_b128 v[122:125], v165 offset:32288
	s_cmp_lg_u32 s25, 4
	s_cselect_b32 s25, s28, 0
	s_waitcnt lgkmcnt(2)
	v_mfma_f32_32x32x16_bf16 v[138:153], v[240:243], v[158:161], v[34:49]
	v_exp_f32_e32 v126, v66
	v_exp_f32_e32 v127, v67
	v_exp_f32_e32 v128, v68
	v_exp_f32_e32 v129, v69
	v_exp_f32_e32 v130, v70
	v_exp_f32_e32 v131, v71
	v_exp_f32_e32 v132, v72
	v_exp_f32_e32 v133, v73
	s_waitcnt lgkmcnt(1)
	v_mfma_f32_32x32x16_bf16 v[82:97], v[244:247], v[158:161], v[34:49]
	v_exp_f32_e32 v134, v74
	v_exp_f32_e32 v135, v75
	v_exp_f32_e32 v136, v76
	v_exp_f32_e32 v137, v77
	v_exp_f32_e32 v177, v78
	v_exp_f32_e32 v178, v79
	v_exp_f32_e32 v179, v80
	v_exp_f32_e32 v185, v81
	v_mfma_f32_32x32x16_bf16 v[138:153], v[106:109], v[154:157], v[138:153]
	v_exp_f32_e32 v80, v50
	v_exp_f32_e32 v81, v51
	v_exp_f32_e32 v186, v52
	v_exp_f32_e32 v187, v53
	v_exp_f32_e32 v194, v54
	v_exp_f32_e32 v195, v55
	v_exp_f32_e32 v196, v56
	v_exp_f32_e32 v197, v57
	s_waitcnt lgkmcnt(0)
	v_mfma_f32_32x32x16_bf16 v[82:97], v[122:125], v[154:157], v[82:97]
	v_exp_f32_e32 v198, v58
	v_exp_f32_e32 v199, v59
	v_exp_f32_e32 v200, v60
	v_exp_f32_e32 v201, v61
	v_exp_f32_e32 v122, v62
	v_exp_f32_e32 v123, v63
	v_exp_f32_e32 v124, v64
	v_exp_f32_e32 v125, v65
	s_cmp_gt_i32 s25, 2
	s_cselect_b32 s26, -3, 2
	s_add_i32 s26, s26, s25
	s_mulk_i32 s26, 0x2400
	v_add_u32_e32 v50, s26, v182
	s_add_i32 s26, s25, 1
	s_cmp_lg_u32 s25, 4
	s_cselect_b32 s25, s26, 0
	s_add_i32 s26, s23, -1
	s_min_u32 s26, s26, s13
	s_lshl_b32 s92, s26, 13
	s_waitcnt vmcnt(3)
	ds_write_b128 v182, v[118:121] offset:9216
	s_waitcnt vmcnt(2)
	ds_write_b128 v50, v[114:117] offset:36864
	s_mul_i32 vcc_lo, s25, 0x2400
	s_add_i32 vcc_lo, vcc_lo, 0xffffdc00
	s_cmp_lg_u32 s25, 0
	s_cselect_b32 vcc_lo, vcc_lo, 0x9000
	v_add_u32_e32 v50, vcc_lo, v163
	ds_read_b128 v[60:63], v50 offset:36864
	ds_read_b128 v[64:67], v50 offset:36896
	ds_read_b128 v[68:71], v50 offset:41472
	ds_read_b128 v[72:75], v50 offset:41504
	ds_read_b128 v[76:79], v50 offset:36928
	ds_read_b128 v[106:109], v50 offset:36960
	ds_read_b128 v[110:113], v50 offset:41536
	ds_read_b128 v[114:117], v50 offset:41568
	s_add_u32 vcc_lo, s100, s92
	s_addc_u32 vcc_hi, s101, 0
	global_load_dwordx4 v[56:59], v248, vcc
	s_lshl_b32 s92, s27, 7
	s_add_u32 vcc_lo, s98, s92
	s_addc_u32 vcc_hi, s99, 0
	global_load_dwordx4 v[52:55], v249, vcc
	s_nop 0
	s_mul_i32 s27, s25, 0x2400
	s_setprio 3
	v_cvt_pk_bf16_f32 v118, v126, v127
	v_cvt_pk_bf16_f32 v119, v128, v129
	v_cvt_pk_bf16_f32 v120, v130, v131
	v_cvt_pk_bf16_f32 v121, v132, v133
	s_waitcnt lgkmcnt(7)
	s_nop 0
	v_mfma_f32_32x32x16_bf16 v[18:33], v[60:63], v[118:121], v[18:33]
	v_add_f32_e32 v50, v126, v127
	v_add_f32_e32 v50, v50, v128
	v_add_f32_e32 v50, v50, v129
	s_waitcnt lgkmcnt(5)
	v_mfma_f32_32x32x16_bf16 v[2:17], v[68:71], v[118:121], v[2:17]
	v_cvt_pk_bf16_f32 v60, v134, v135
	v_cvt_pk_bf16_f32 v61, v136, v137
	v_cvt_pk_bf16_f32 v62, v177, v178
	v_cvt_pk_bf16_f32 v63, v179, v185
	v_add_f32_e32 v50, v50, v130
	v_add_f32_e32 v50, v50, v131
	v_add_f32_e32 v50, v50, v132
	v_add_f32_e32 v50, v50, v133
	s_nop 0
	v_mfma_f32_32x32x16_bf16 v[18:33], v[64:67], v[60:63], v[18:33]
	v_add_f32_e32 v50, v50, v134
	v_add_f32_e32 v50, v50, v135
	v_add_f32_e32 v50, v50, v136
	v_add_f32_e32 v50, v50, v137
	s_waitcnt lgkmcnt(4)
	v_mfma_f32_32x32x16_bf16 v[2:17], v[72:75], v[60:63], v[2:17]
	v_cvt_pk_bf16_f32 v64, v80, v81
	v_cvt_pk_bf16_f32 v65, v186, v187
	v_cvt_pk_bf16_f32 v66, v194, v195
	v_cvt_pk_bf16_f32 v67, v196, v197
	v_add_f32_e32 v50, v50, v177
	v_add_f32_e32 v50, v50, v178
	v_add_f32_e32 v50, v50, v179
	v_add_f32_e32 v50, v50, v185
	s_waitcnt lgkmcnt(3)
	v_mfma_f32_32x32x16_bf16 v[18:33], v[76:79], v[64:67], v[18:33]
	v_add_f32_e32 v50, v50, v80
	v_add_f32_e32 v50, v50, v81
	v_add_f32_e32 v50, v50, v186
	v_add_f32_e32 v50, v50, v187
	s_waitcnt lgkmcnt(1)
	v_mfma_f32_32x32x16_bf16 v[2:17], v[110:113], v[64:67], v[2:17]
	v_cvt_pk_bf16_f32 v60, v198, v199
	v_cvt_pk_bf16_f32 v61, v200, v201
	v_cvt_pk_bf16_f32 v62, v122, v123
	v_cvt_pk_bf16_f32 v63, v124, v125
	v_add_f32_e32 v50, v50, v194
	v_add_f32_e32 v50, v50, v195
	v_add_f32_e32 v50, v50, v196
	v_add_f32_e32 v50, v50, v197
	s_nop 0
	v_mfma_f32_32x32x16_bf16 v[18:33], v[106:109], v[60:63], v[18:33]
	v_add_f32_e32 v50, v50, v198
	v_add_f32_e32 v50, v50, v199
	v_add_f32_e32 v50, v50, v200
	v_add_f32_e32 v50, v50, v201
	s_waitcnt lgkmcnt(0)
	v_mfma_f32_32x32x16_bf16 v[2:17], v[114:117], v[60:63], v[2:17]
	v_add_f32_e32 v50, v50, v122
	v_add_f32_e32 v50, v50, v123
	v_add_f32_e32 v50, v50, v124
	v_add_f32_e32 v50, v50, v125
	s_setprio 2
	s_waitcnt lgkmcnt(0)
	s_barrier
	ds_read_b128 v[240:243], v165
	ds_read_b128 v[244:247], v165 offset:4608
	ds_read_b128 v[68:71], v165 offset:32
	ds_read_b128 v[72:75], v165 offset:4640
	v_add_f32_e32 v1, v1, v176
	v_exp_f32_e32 v176, v138
	v_exp_f32_e32 v177, v139
	v_exp_f32_e32 v178, v140
	v_exp_f32_e32 v179, v141
	v_exp_f32_e32 v185, v142
	v_exp_f32_e32 v186, v143
	v_exp_f32_e32 v187, v144
	v_exp_f32_e32 v194, v145
	s_waitcnt lgkmcnt(2)
	v_mfma_f32_32x32x16_bf16 v[122:137], v[240:243], v[158:161], v[34:49]
	v_mfma_f32_32x32x16_bf16 v[106:121], v[244:247], v[158:161], v[34:49]
	v_exp_f32_e32 v195, v146
	v_exp_f32_e32 v196, v147
	v_exp_f32_e32 v197, v148
	v_exp_f32_e32 v198, v149
	v_exp_f32_e32 v146, v150
	v_exp_f32_e32 v147, v151
	v_exp_f32_e32 v148, v152
	v_exp_f32_e32 v149, v153
	s_waitcnt lgkmcnt(1)
	v_mfma_f32_32x32x16_bf16 v[122:137], v[68:71], v[154:157], v[122:137]
	v_exp_f32_e32 v150, v82
	v_exp_f32_e32 v151, v83
	v_exp_f32_e32 v152, v84
	v_exp_f32_e32 v153, v85
	v_exp_f32_e32 v199, v86
	v_exp_f32_e32 v200, v87
	v_exp_f32_e32 v201, v88
	v_exp_f32_e32 v202, v89
	s_waitcnt lgkmcnt(0)
	v_mfma_f32_32x32x16_bf16 v[106:121], v[72:75], v[154:157], v[106:121]
	v_exp_f32_e32 v203, v90
	v_exp_f32_e32 v204, v91
	v_exp_f32_e32 v205, v92
	v_exp_f32_e32 v206, v93
	v_exp_f32_e32 v207, v94
	v_exp_f32_e32 v208, v95
	v_exp_f32_e32 v209, v96
	v_exp_f32_e32 v210, v97
	v_add_u32_e32 v88, s27, v163
	ds_read_b128 v[240:243], v165 offset:9216
	ds_read_b128 v[244:247], v165 offset:13824
	ds_read_b128 v[60:63], v88 offset:41472
	ds_read_b128 v[64:67], v88 offset:36864
	ds_read_b128 v[68:71], v88 offset:36896
	ds_read_b128 v[72:75], v88 offset:41504
	ds_read_b128 v[76:79], v88 offset:36928
	ds_read_b128 v[80:83], v88 offset:41536
	ds_read_b128 v[84:87], v88 offset:36960
	ds_read_b128 v[88:91], v88 offset:41568
	s_cmp_gt_i32 s25, 2
	s_cselect_b32 s28, -3, 2
	s_add_i32 s28, s28, s25
	s_mulk_i32 s28, 0x2400
	s_min_u32 s27, s23, s13
	v_add_u32_e32 v51, s28, v182
	s_lshl_b32 s92, s27, 13
	s_waitcnt vmcnt(3)
	ds_write_b128 v182, v[98:101] offset:18432
	s_waitcnt vmcnt(2)
	ds_write_b128 v51, v[102:105] offset:36864
	v_add_f32_e32 v1, v1, v50
	s_add_u32 vcc_lo, s100, s92
	s_addc_u32 vcc_hi, s101, 0
	global_load_dwordx4 v[138:141], v248, vcc
	s_lshl_b32 s92, s26, 7
	s_add_u32 vcc_lo, s98, s92
	s_addc_u32 vcc_hi, s99, 0
	global_load_dwordx4 v[142:145], v249, vcc
	s_setprio 1
	v_mov_b32_e32 v51, v122
	v_cvt_pk_bf16_f32 v92, v176, v177
	v_cvt_pk_bf16_f32 v93, v178, v179
	v_cvt_pk_bf16_f32 v94, v185, v186
	v_cvt_pk_bf16_f32 v95, v187, v194
	s_waitcnt lgkmcnt(8)
	s_nop 0
	v_mfma_f32_32x32x16_bf16 v[18:33], v[64:67], v[92:95], v[18:33]
	v_max3_f32 v51, v51, v123, v124
	v_max3_f32 v51, v51, v125, v126
	v_add_f32_e32 v50, v176, v177
	v_add_f32_e32 v50, v50, v178
	v_add_f32_e32 v50, v50, v179
	s_nop 0
	v_mfma_f32_32x32x16_bf16 v[2:17], v[60:63], v[92:95], v[2:17]
	v_cvt_pk_bf16_f32 v64, v195, v196
	v_cvt_pk_bf16_f32 v65, v197, v198
	v_cvt_pk_bf16_f32 v66, v146, v147
	v_cvt_pk_bf16_f32 v67, v148, v149
	v_max3_f32 v51, v51, v127, v128
	v_max3_f32 v51, v51, v129, v130
	v_add_f32_e32 v50, v50, v185
	v_add_f32_e32 v50, v50, v186
	v_add_f32_e32 v50, v50, v187
	v_add_f32_e32 v50, v50, v194
	s_waitcnt lgkmcnt(7)
	v_mfma_f32_32x32x16_bf16 v[18:33], v[68:71], v[64:67], v[18:33]
	v_max3_f32 v51, v51, v131, v132
	v_max3_f32 v51, v51, v133, v134
	v_add_f32_e32 v50, v50, v195
	v_add_f32_e32 v50, v50, v196
	v_add_f32_e32 v50, v50, v197
	v_add_f32_e32 v50, v50, v198
	s_waitcnt lgkmcnt(6)
	v_mfma_f32_32x32x16_bf16 v[2:17], v[72:75], v[64:67], v[2:17]
	v_cvt_pk_bf16_f32 v60, v150, v151
	v_cvt_pk_bf16_f32 v61, v152, v153
	v_cvt_pk_bf16_f32 v62, v199, v200
	v_cvt_pk_bf16_f32 v63, v201, v202
	v_max3_f32 v51, v51, v135, v136
	v_max3_f32 v51, v51, v137, v106
	v_add_f32_e32 v50, v50, v146
	v_add_f32_e32 v50, v50, v147
	v_add_f32_e32 v50, v50, v148
	v_add_f32_e32 v50, v50, v149
	s_waitcnt lgkmcnt(5)
	v_mfma_f32_32x32x16_bf16 v[18:33], v[76:79], v[60:63], v[18:33]
	v_max3_f32 v51, v51, v107, v108
	v_max3_f32 v51, v51, v109, v110
	v_add_f32_e32 v50, v50, v150
	v_add_f32_e32 v50, v50, v151
	v_add_f32_e32 v50, v50, v152
	v_add_f32_e32 v50, v50, v153
	s_waitcnt lgkmcnt(4)
	v_mfma_f32_32x32x16_bf16 v[2:17], v[80:83], v[60:63], v[2:17]
	v_cvt_pk_bf16_f32 v64, v203, v204
	v_cvt_pk_bf16_f32 v65, v205, v206
	v_cvt_pk_bf16_f32 v66, v207, v208
	v_cvt_pk_bf16_f32 v67, v209, v210
	v_max3_f32 v51, v51, v111, v112
	v_max3_f32 v51, v51, v113, v114
	v_add_f32_e32 v50, v50, v199
	v_add_f32_e32 v50, v50, v200
	v_add_f32_e32 v50, v50, v201
	v_add_f32_e32 v50, v50, v202
	s_waitcnt lgkmcnt(3)
	v_mfma_f32_32x32x16_bf16 v[18:33], v[84:87], v[64:67], v[18:33]
	v_max3_f32 v51, v51, v115, v116
	v_max3_f32 v51, v51, v117, v118
	v_add_f32_e32 v50, v50, v203
	v_add_f32_e32 v50, v50, v204
	v_add_f32_e32 v50, v50, v205
	v_add_f32_e32 v50, v50, v206
	s_waitcnt lgkmcnt(2)
	v_mfma_f32_32x32x16_bf16 v[2:17], v[88:91], v[64:67], v[2:17]
	v_max3_f32 v51, v51, v119, v120
	v_max3_f32 v51, v51, v121, v121
	v_add_f32_e32 v50, v50, v207
	v_add_f32_e32 v50, v50, v208
	v_add_f32_e32 v50, v50, v209
	v_add_f32_e32 v50, v50, v210
	s_setprio 0
	ds_read_b128 v[146:149], v165 offset:9248
	ds_read_b128 v[60:63], v165 offset:13856
	v_add_f32_e32 v50, v1, v50
	v_mov_b32_e32 v1, v51
	s_nop 1
	v_permlane32_swap_b32_e32 v51, v1
	v_max_f32_e32 v1, v1, v1
	v_max_f32_e32 v51, v51, v51
	v_max_f32_e32 v1, v51, v1
	v_cmp_lt_f32_e32 vcc, s52, v1
	s_cbranch_vccz .LBB0_643
	v_max_f32_e32 v1, v1, v1
	v_max_f32_e32 v68, 0, v1
	v_add_f32_e32 v183, v183, v68
	v_xor_b32_e32 v34, 0x80000000, v183
	v_pk_add_f32 v[122:123], v[122:123], v[68:69] op_sel_hi:[1,0] neg_lo:[0,1] neg_hi:[0,1]
	v_pk_add_f32 v[106:107], v[106:107], v[68:69] op_sel_hi:[1,0] neg_lo:[0,1] neg_hi:[0,1]
	v_pk_add_f32 v[124:125], v[124:125], v[68:69] op_sel_hi:[1,0] neg_lo:[0,1] neg_hi:[0,1]
	v_pk_add_f32 v[108:109], v[108:109], v[68:69] op_sel_hi:[1,0] neg_lo:[0,1] neg_hi:[0,1]
	v_pk_add_f32 v[126:127], v[126:127], v[68:69] op_sel_hi:[1,0] neg_lo:[0,1] neg_hi:[0,1]
	v_pk_add_f32 v[110:111], v[110:111], v[68:69] op_sel_hi:[1,0] neg_lo:[0,1] neg_hi:[0,1]
	v_pk_add_f32 v[128:129], v[128:129], v[68:69] op_sel_hi:[1,0] neg_lo:[0,1] neg_hi:[0,1]
	v_pk_add_f32 v[112:113], v[112:113], v[68:69] op_sel_hi:[1,0] neg_lo:[0,1] neg_hi:[0,1]
	v_pk_add_f32 v[130:131], v[130:131], v[68:69] op_sel_hi:[1,0] neg_lo:[0,1] neg_hi:[0,1]
	v_pk_add_f32 v[114:115], v[114:115], v[68:69] op_sel_hi:[1,0] neg_lo:[0,1] neg_hi:[0,1]
	v_pk_add_f32 v[132:133], v[132:133], v[68:69] op_sel_hi:[1,0] neg_lo:[0,1] neg_hi:[0,1]
	v_pk_add_f32 v[116:117], v[116:117], v[68:69] op_sel_hi:[1,0] neg_lo:[0,1] neg_hi:[0,1]
	v_pk_add_f32 v[134:135], v[134:135], v[68:69] op_sel_hi:[1,0] neg_lo:[0,1] neg_hi:[0,1]
	v_pk_add_f32 v[118:119], v[118:119], v[68:69] op_sel_hi:[1,0] neg_lo:[0,1] neg_hi:[0,1]
	v_pk_add_f32 v[136:137], v[136:137], v[68:69] op_sel_hi:[1,0] neg_lo:[0,1] neg_hi:[0,1]
	v_pk_add_f32 v[120:121], v[120:121], v[68:69] op_sel_hi:[1,0] neg_lo:[0,1] neg_hi:[0,1]
	v_exp_f32_e64 v68, -v68
	v_mov_b32_e32 v35, v34
	v_mov_b32_e32 v36, v34
	v_mov_b32_e32 v37, v34
	v_mov_b32_e32 v38, v34
	v_mov_b32_e32 v39, v34
	v_mov_b32_e32 v40, v34
	v_mov_b32_e32 v41, v34
	v_mov_b32_e32 v42, v34
	v_mov_b32_e32 v43, v34
	v_mov_b32_e32 v44, v34
	v_mov_b32_e32 v45, v34
	v_mov_b32_e32 v46, v34
	v_mov_b32_e32 v47, v34
	v_mov_b32_e32 v48, v34
	v_mov_b32_e32 v49, v34
	s_nop 11
	v_pk_mul_f32 v[32:33], v[32:33], v[68:69] op_sel_hi:[1,0]
	v_pk_mul_f32 v[30:31], v[30:31], v[68:69] op_sel_hi:[1,0]
	v_pk_mul_f32 v[28:29], v[28:29], v[68:69] op_sel_hi:[1,0]
	v_pk_mul_f32 v[26:27], v[26:27], v[68:69] op_sel_hi:[1,0]
	v_pk_mul_f32 v[24:25], v[24:25], v[68:69] op_sel_hi:[1,0]
	v_pk_mul_f32 v[22:23], v[22:23], v[68:69] op_sel_hi:[1,0]
	v_pk_mul_f32 v[20:21], v[20:21], v[68:69] op_sel_hi:[1,0]
	v_pk_mul_f32 v[18:19], v[18:19], v[68:69] op_sel_hi:[1,0]
	v_pk_mul_f32 v[16:17], v[16:17], v[68:69] op_sel_hi:[1,0]
	v_pk_mul_f32 v[14:15], v[14:15], v[68:69] op_sel_hi:[1,0]
	v_pk_mul_f32 v[12:13], v[12:13], v[68:69] op_sel_hi:[1,0]
	v_pk_mul_f32 v[10:11], v[10:11], v[68:69] op_sel_hi:[1,0]
	v_pk_mul_f32 v[8:9], v[8:9], v[68:69] op_sel_hi:[1,0]
	v_pk_mul_f32 v[6:7], v[6:7], v[68:69] op_sel_hi:[1,0]
	v_pk_mul_f32 v[4:5], v[4:5], v[68:69] op_sel_hi:[1,0]
	v_pk_mul_f32 v[2:3], v[2:3], v[68:69] op_sel_hi:[1,0]
	v_mul_f32_e32 v50, v50, v68

.LBB0_661:
	s_mul_i32 vcc_lo, s27, 0x2400
	s_add_i32 vcc_lo, vcc_lo, 0xffffdc00
	s_cmp_lg_u32 s27, 0
	s_cselect_b32 vcc_lo, vcc_lo, 0x9000
	v_add_u32_e32 v1, vcc_lo, v195
	ds_read_b128 v[10:13], v1 offset:36864
	ds_read_b128 v[66:69], v1 offset:36896
	ds_read_b128 v[70:73], v1 offset:41472
	ds_read_b128 v[74:77], v1 offset:41504
	ds_read_b128 v[128:131], v1 offset:36928
	ds_read_b128 v[132:135], v1 offset:36960
	ds_read_b128 v[148:151], v1 offset:41536
	ds_read_b128 v[160:163], v1 offset:41568
	s_add_i32 s26, s13, -7
	s_lshl_b32 s92, s26, 13
	s_add_u32 vcc_lo, s100, s92
	s_addc_u32 vcc_hi, s101, 0
	global_load_dwordx4 v[2:5], v248, vcc
	s_add_i32 s26, s13, -8
	s_lshl_b32 s92, s26, 7
	s_add_u32 vcc_lo, s98, s92
	s_addc_u32 vcc_hi, s99, 0
	global_load_dwordx4 v[6:9], v249, vcc
	s_mul_i32 s28, s27, 0x2400
	s_add_i32 s26, s13, -7
	s_setprio 3
	v_cvt_pk_bf16_f32 v210, v116, v117
	v_cvt_pk_bf16_f32 v211, v118, v119
	v_cvt_pk_bf16_f32 v212, v112, v113
	v_cvt_pk_bf16_f32 v213, v114, v115
	s_waitcnt lgkmcnt(7)
	s_nop 0
	v_mfma_f32_32x32x16_bf16 v[16:31], v[10:13], v[210:213], v[16:31]
	v_add_f32_e32 v1, v116, v117
	v_add_f32_e32 v1, v1, v118
	v_add_f32_e32 v1, v1, v119
	s_waitcnt lgkmcnt(5)
	v_mfma_f32_32x32x16_bf16 v[32:47], v[70:73], v[210:213], v[32:47]
	v_cvt_pk_bf16_f32 v10, v187, v186
	v_cvt_pk_bf16_f32 v11, v185, v184
	v_cvt_pk_bf16_f32 v12, v147, v146
	v_cvt_pk_bf16_f32 v13, v145, v144
	v_add_f32_e32 v1, v1, v112
	v_add_f32_e32 v1, v1, v113
	v_add_f32_e32 v1, v1, v114
	v_add_f32_e32 v1, v1, v115
	s_nop 0
	v_mfma_f32_32x32x16_bf16 v[16:31], v[66:69], v[10:13], v[16:31]
	v_add_f32_e32 v1, v1, v187
	v_add_f32_e32 v1, v1, v186
	v_add_f32_e32 v1, v1, v185
	v_add_f32_e32 v1, v1, v184
	s_waitcnt lgkmcnt(4)
	v_mfma_f32_32x32x16_bf16 v[32:47], v[74:77], v[10:13], v[32:47]
	v_cvt_pk_bf16_f32 v66, v143, v142
	v_cvt_pk_bf16_f32 v67, v141, v140
	v_cvt_pk_bf16_f32 v68, v139, v138
	v_cvt_pk_bf16_f32 v69, v137, v136
	v_add_f32_e32 v1, v1, v147
	v_add_f32_e32 v1, v1, v146
	v_add_f32_e32 v1, v1, v145
	v_add_f32_e32 v1, v1, v144
	s_waitcnt lgkmcnt(3)
	v_mfma_f32_32x32x16_bf16 v[16:31], v[128:131], v[66:69], v[16:31]
	v_add_f32_e32 v1, v1, v143
	v_add_f32_e32 v1, v1, v142
	v_add_f32_e32 v1, v1, v141
	v_add_f32_e32 v1, v1, v140
	s_waitcnt lgkmcnt(1)
	v_mfma_f32_32x32x16_bf16 v[32:47], v[148:151], v[66:69], v[32:47]
	v_cvt_pk_bf16_f32 v10, v123, v122
	v_cvt_pk_bf16_f32 v11, v121, v120
	v_cvt_pk_bf16_f32 v12, v127, v126
	v_cvt_pk_bf16_f32 v13, v125, v124
	v_add_f32_e32 v1, v1, v139
	v_add_f32_e32 v1, v1, v138
	v_add_f32_e32 v1, v1, v137
	v_add_f32_e32 v1, v1, v136
	s_nop 0
	v_mfma_f32_32x32x16_bf16 v[16:31], v[132:135], v[10:13], v[16:31]
	v_add_f32_e32 v1, v1, v123
	v_add_f32_e32 v1, v1, v122
	v_add_f32_e32 v1, v1, v121
	v_add_f32_e32 v1, v1, v120
	s_waitcnt lgkmcnt(0)
	v_mfma_f32_32x32x16_bf16 v[32:47], v[160:163], v[10:13], v[32:47]
	v_add_f32_e32 v1, v1, v127
	v_add_f32_e32 v1, v1, v126
	v_add_f32_e32 v1, v1, v125
	v_add_f32_e32 v1, v1, v124
	s_setprio 2
	s_waitcnt lgkmcnt(0)
	s_barrier
	ds_read_b128 v[240:243], v195 offset:18432
	ds_read_b128 v[244:247], v195 offset:23040
	ds_read_b128 v[66:69], v195 offset:18464
	ds_read_b128 v[74:77], v195 offset:23072
	ds_read_b128 v[144:147], v195 offset:18496
	ds_read_b128 v[148:151], v195 offset:18528
	ds_read_b128 v[160:163], v195 offset:23104
	ds_read_b128 v[184:187], v195 offset:23136
	v_exp_f32_e32 v166, v96
	v_exp_f32_e32 v167, v97
	v_exp_f32_e32 v210, v98
	v_exp_f32_e32 v211, v99
	s_waitcnt lgkmcnt(6)
	v_mfma_f32_32x32x16_bf16 v[128:143], v[240:243], v[180:183], v[48:63]
	s_waitcnt lgkmcnt(5)
	v_mfma_f32_32x32x16_bf16 v[112:127], v[244:247], v[180:183], v[48:63]
	v_exp_f32_e32 v212, v100
	v_exp_f32_e32 v213, v101
	v_exp_f32_e32 v214, v102
	v_exp_f32_e32 v215, v103
	v_mfma_f32_32x32x16_bf16 v[128:143], v[66:69], v[176:179], v[128:143]
	v_exp_f32_e32 v100, v104
	v_exp_f32_e32 v101, v105
	v_exp_f32_e32 v102, v106
	v_exp_f32_e32 v103, v107
	s_waitcnt lgkmcnt(4)
	v_mfma_f32_32x32x16_bf16 v[112:127], v[74:77], v[176:179], v[112:127]
	v_exp_f32_e32 v104, v108
	v_exp_f32_e32 v105, v109
	v_exp_f32_e32 v106, v110
	v_exp_f32_e32 v107, v111
	s_waitcnt lgkmcnt(3)
	v_mfma_f32_32x32x16_bf16 v[128:143], v[144:147], v[172:175], v[128:143]
	v_exp_f32_e32 v108, v80
	v_exp_f32_e32 v109, v81
	v_exp_f32_e32 v110, v82
	v_exp_f32_e32 v111, v83
	s_waitcnt lgkmcnt(1)
	v_mfma_f32_32x32x16_bf16 v[112:127], v[160:163], v[172:175], v[112:127]
	v_exp_f32_e32 v144, v84
	v_exp_f32_e32 v145, v85
	v_exp_f32_e32 v146, v86
	v_exp_f32_e32 v147, v87
	v_mfma_f32_32x32x16_bf16 v[128:143], v[148:151], v[168:171], v[128:143]
	v_exp_f32_e32 v216, v88
	v_exp_f32_e32 v217, v89
	v_exp_f32_e32 v218, v90
	v_exp_f32_e32 v219, v91
	s_waitcnt lgkmcnt(0)
	v_mfma_f32_32x32x16_bf16 v[112:127], v[184:187], v[168:171], v[112:127]
	v_exp_f32_e32 v148, v92
	v_exp_f32_e32 v149, v93
	v_exp_f32_e32 v150, v94
	v_exp_f32_e32 v151, v95
	v_add_f32_e32 v1, v64, v1
	v_add_u32_e32 v92, s28, v195
	ds_read_b128 v[240:243], v195 offset:27648
	ds_read_b128 v[244:247], v195 offset:32256
	ds_read_b128 v[64:67], v92 offset:41472
	ds_read_b128 v[68:71], v92 offset:36864
	ds_read_b128 v[72:75], v92 offset:36896
	ds_read_b128 v[76:79], v92 offset:41504
	ds_read_b128 v[80:83], v92 offset:36928
	ds_read_b128 v[84:87], v92 offset:41536
	ds_read_b128 v[88:91], v92 offset:36960
	ds_read_b128 v[92:95], v92 offset:41568
	s_cmp_gt_i32 s27, 2
	s_cselect_b32 s29, -3, 2
	s_add_i32 s29, s29, s27
	s_add_i32 s28, s13, -6
	s_mulk_i32 s29, 0x2400
	s_min_u32 s28, s28, s12
	v_add_u32_e32 v10, s29, v208
	s_min_u32 s26, s26, s12
	s_lshl_b32 s92, s28, 13
	s_waitcnt vmcnt(3)
	ds_write_b128 v208, v[152:155]
	s_waitcnt vmcnt(2)
	ds_write_b128 v10, v[156:159] offset:36864
	s_add_u32 vcc_lo, s100, s92
	s_addc_u32 vcc_hi, s101, 0
	global_load_dwordx4 v[10:13], v248, vcc
	s_lshl_b32 s92, s26, 7
	s_add_u32 vcc_lo, s98, s92
	s_addc_u32 vcc_hi, s99, 0
	global_load_dwordx4 v[160:163], v249, vcc
	s_add_i32 s29, s27, 1
	s_setprio 1
	v_cvt_pk_bf16_f32 v96, v166, v167
	v_cvt_pk_bf16_f32 v97, v210, v211
	v_cvt_pk_bf16_f32 v98, v212, v213
	v_cvt_pk_bf16_f32 v99, v214, v215
	s_waitcnt lgkmcnt(8)
	s_nop 0
	v_mfma_f32_32x32x16_bf16 v[16:31], v[68:71], v[96:99], v[16:31]
	v_add_f32_e32 v184, v166, v167
	v_add_f32_e32 v184, v184, v210
	v_add_f32_e32 v184, v184, v211
	s_nop 0
	v_mfma_f32_32x32x16_bf16 v[32:47], v[64:67], v[96:99], v[32:47]
	v_cvt_pk_bf16_f32 v68, v100, v101
	v_cvt_pk_bf16_f32 v69, v102, v103
	v_cvt_pk_bf16_f32 v70, v104, v105
	v_cvt_pk_bf16_f32 v71, v106, v107
	v_add_f32_e32 v184, v184, v212
	v_add_f32_e32 v184, v184, v213
	v_add_f32_e32 v184, v184, v214
	v_add_f32_e32 v184, v184, v215
	s_waitcnt lgkmcnt(7)
	v_mfma_f32_32x32x16_bf16 v[16:31], v[72:75], v[68:71], v[16:31]
	v_add_f32_e32 v184, v184, v100
	v_add_f32_e32 v184, v184, v101
	v_add_f32_e32 v184, v184, v102
	v_add_f32_e32 v184, v184, v103
	s_waitcnt lgkmcnt(6)
	v_mfma_f32_32x32x16_bf16 v[32:47], v[76:79], v[68:71], v[32:47]
	v_cvt_pk_bf16_f32 v64, v108, v109
	v_cvt_pk_bf16_f32 v65, v110, v111
	v_cvt_pk_bf16_f32 v66, v144, v145
	v_cvt_pk_bf16_f32 v67, v146, v147
	v_add_f32_e32 v184, v184, v104
	v_add_f32_e32 v184, v184, v105
	v_add_f32_e32 v184, v184, v106
	v_add_f32_e32 v184, v184, v107
	s_waitcnt lgkmcnt(5)
	v_mfma_f32_32x32x16_bf16 v[16:31], v[80:83], v[64:67], v[16:31]
	v_add_f32_e32 v184, v184, v108
	v_add_f32_e32 v184, v184, v109
	v_add_f32_e32 v184, v184, v110
	v_add_f32_e32 v184, v184, v111
	s_waitcnt lgkmcnt(4)
	v_mfma_f32_32x32x16_bf16 v[32:47], v[84:87], v[64:67], v[32:47]
	v_cvt_pk_bf16_f32 v68, v216, v217
	v_cvt_pk_bf16_f32 v69, v218, v219
	v_cvt_pk_bf16_f32 v70, v148, v149
	v_cvt_pk_bf16_f32 v71, v150, v151
	v_add_f32_e32 v184, v184, v144
	v_add_f32_e32 v184, v184, v145
	v_add_f32_e32 v184, v184, v146
	v_add_f32_e32 v184, v184, v147
	s_waitcnt lgkmcnt(3)
	v_mfma_f32_32x32x16_bf16 v[16:31], v[88:91], v[68:71], v[16:31]
	v_add_f32_e32 v184, v184, v216
	v_add_f32_e32 v184, v184, v217
	v_add_f32_e32 v184, v184, v218
	v_add_f32_e32 v184, v184, v219
	s_waitcnt lgkmcnt(2)
	v_mfma_f32_32x32x16_bf16 v[32:47], v[92:95], v[68:71], v[32:47]
	v_add_f32_e32 v184, v184, v148
	v_add_f32_e32 v184, v184, v149
	v_add_f32_e32 v184, v184, v150
	v_add_f32_e32 v184, v184, v151
	s_setprio 0
	ds_read_b128 v[68:71], v195 offset:27680
	ds_read_b128 v[76:79], v195 offset:32288
	ds_read_b128 v[80:83], v195 offset:27712
	ds_read_b128 v[84:87], v195 offset:27744
	ds_read_b128 v[88:91], v195 offset:32320
	ds_read_b128 v[92:95], v195 offset:32352
	s_cmp_lg_u32 s27, 4
	s_cselect_b32 s26, s29, 0
	s_waitcnt lgkmcnt(6)
	v_mfma_f32_32x32x16_bf16 v[144:159], v[240:243], v[180:183], v[48:63]
	v_exp_f32_e32 v166, v128
	v_exp_f32_e32 v167, v129
	v_exp_f32_e32 v185, v130
	v_exp_f32_e32 v186, v131
	s_waitcnt lgkmcnt(5)
	v_mfma_f32_32x32x16_bf16 v[96:111], v[244:247], v[180:183], v[48:63]
	v_exp_f32_e32 v128, v132
	v_exp_f32_e32 v129, v133
	v_exp_f32_e32 v130, v134
	v_exp_f32_e32 v131, v135
	v_mfma_f32_32x32x16_bf16 v[144:159], v[68:71], v[176:179], v[144:159]
	v_exp_f32_e32 v132, v136
	v_exp_f32_e32 v133, v137
	v_exp_f32_e32 v134, v138
	v_exp_f32_e32 v135, v139
	s_waitcnt lgkmcnt(4)
	v_mfma_f32_32x32x16_bf16 v[96:111], v[76:79], v[176:179], v[96:111]
	v_exp_f32_e32 v136, v140
	v_exp_f32_e32 v137, v141
	v_exp_f32_e32 v138, v142
	v_exp_f32_e32 v139, v143
	s_waitcnt lgkmcnt(3)
	v_mfma_f32_32x32x16_bf16 v[144:159], v[80:83], v[172:175], v[144:159]
	v_exp_f32_e32 v140, v112
	v_exp_f32_e32 v141, v113
	v_exp_f32_e32 v142, v114
	v_exp_f32_e32 v143, v115
	s_waitcnt lgkmcnt(1)
	v_mfma_f32_32x32x16_bf16 v[96:111], v[88:91], v[172:175], v[96:111]
	v_exp_f32_e32 v187, v116
	v_exp_f32_e32 v210, v117
	v_exp_f32_e32 v211, v118
	v_exp_f32_e32 v212, v119
	v_mfma_f32_32x32x16_bf16 v[144:159], v[84:87], v[168:171], v[144:159]
	v_exp_f32_e32 v116, v120
	v_exp_f32_e32 v117, v121
	v_exp_f32_e32 v118, v122
	v_exp_f32_e32 v119, v123
	s_waitcnt lgkmcnt(0)
	v_mfma_f32_32x32x16_bf16 v[96:111], v[92:95], v[168:171], v[96:111]
	v_exp_f32_e32 v120, v124
	v_exp_f32_e32 v121, v125
	v_exp_f32_e32 v122, v126
	v_exp_f32_e32 v123, v127
	s_cmp_gt_i32 s26, 2
	s_cselect_b32 s27, -3, 2
	s_add_i32 s27, s27, s26
	s_mulk_i32 s27, 0x2400
	s_waitcnt vmcnt(3)
	ds_write_b128 v208, v[2:5] offset:9216
	v_add_u32_e32 v2, s27, v208
	s_add_i32 s27, s26, 1
	s_cmp_lg_u32 s26, 4
	s_cselect_b32 s26, s27, 0
	s_add_i32 s27, s13, -5
	s_min_u32 s27, s27, s12
	s_lshl_b32 s92, s27, 13
	s_waitcnt vmcnt(2)
	ds_write_b128 v2, v[6:9] offset:36864
	s_mul_i32 vcc_lo, s26, 0x2400
	s_add_i32 vcc_lo, vcc_lo, 0xffffdc00
	s_cmp_lg_u32 s26, 0
	s_cselect_b32 vcc_lo, vcc_lo, 0x9000
	v_add_u32_e32 v92, vcc_lo, v195
	ds_read_b128 v[64:67], v92 offset:36864
	ds_read_b128 v[68:71], v92 offset:36896
	ds_read_b128 v[72:75], v92 offset:41472
	ds_read_b128 v[76:79], v92 offset:41504
	ds_read_b128 v[80:83], v92 offset:36928
	ds_read_b128 v[84:87], v92 offset:36960
	ds_read_b128 v[88:91], v92 offset:41536
	ds_read_b128 v[92:95], v92 offset:41568
	s_add_u32 vcc_lo, s100, s92
	s_addc_u32 vcc_hi, s101, 0
	global_load_dwordx4 v[6:9], v248, vcc
	s_lshl_b32 s92, s28, 7
	s_add_u32 vcc_lo, s98, s92
	s_addc_u32 vcc_hi, s99, 0
	global_load_dwordx4 v[2:5], v249, vcc
	s_nop 0
	s_mul_i32 s28, s26, 0x2400
	s_setprio 3
	v_cvt_pk_bf16_f32 v112, v166, v167
	v_cvt_pk_bf16_f32 v113, v185, v186
	v_cvt_pk_bf16_f32 v114, v128, v129
	v_cvt_pk_bf16_f32 v115, v130, v131
	s_waitcnt lgkmcnt(7)
	s_nop 0
	v_mfma_f32_32x32x16_bf16 v[16:31], v[64:67], v[112:115], v[16:31]
	v_add_f32_e32 v213, v166, v167
	v_add_f32_e32 v213, v213, v185
	v_add_f32_e32 v213, v213, v186
	s_waitcnt lgkmcnt(5)
	v_mfma_f32_32x32x16_bf16 v[32:47], v[72:75], v[112:115], v[32:47]
	v_cvt_pk_bf16_f32 v64, v132, v133
	v_cvt_pk_bf16_f32 v65, v134, v135
	v_cvt_pk_bf16_f32 v66, v136, v137
	v_cvt_pk_bf16_f32 v67, v138, v139
	v_add_f32_e32 v213, v213, v128
	v_add_f32_e32 v213, v213, v129
	v_add_f32_e32 v213, v213, v130
	v_add_f32_e32 v213, v213, v131
	s_nop 0
	v_mfma_f32_32x32x16_bf16 v[16:31], v[68:71], v[64:67], v[16:31]
	v_add_f32_e32 v213, v213, v132
	v_add_f32_e32 v213, v213, v133
	v_add_f32_e32 v213, v213, v134
	v_add_f32_e32 v213, v213, v135
	s_waitcnt lgkmcnt(4)
	v_mfma_f32_32x32x16_bf16 v[32:47], v[76:79], v[64:67], v[32:47]
	v_cvt_pk_bf16_f32 v68, v140, v141
	v_cvt_pk_bf16_f32 v69, v142, v143
	v_cvt_pk_bf16_f32 v70, v187, v210
	v_cvt_pk_bf16_f32 v71, v211, v212
	v_add_f32_e32 v213, v213, v136
	v_add_f32_e32 v213, v213, v137
	v_add_f32_e32 v213, v213, v138
	v_add_f32_e32 v213, v213, v139
	s_waitcnt lgkmcnt(3)
	v_mfma_f32_32x32x16_bf16 v[16:31], v[80:83], v[68:71], v[16:31]
	v_add_f32_e32 v213, v213, v140
	v_add_f32_e32 v213, v213, v141
	v_add_f32_e32 v213, v213, v142
	v_add_f32_e32 v213, v213, v143
	s_waitcnt lgkmcnt(1)
	v_mfma_f32_32x32x16_bf16 v[32:47], v[88:91], v[68:71], v[32:47]
	v_cvt_pk_bf16_f32 v64, v116, v117
	v_cvt_pk_bf16_f32 v65, v118, v119
	v_cvt_pk_bf16_f32 v66, v120, v121
	v_cvt_pk_bf16_f32 v67, v122, v123
	v_add_f32_e32 v213, v213, v187
	v_add_f32_e32 v213, v213, v210
	v_add_f32_e32 v213, v213, v211
	v_add_f32_e32 v213, v213, v212
	s_nop 0
	v_mfma_f32_32x32x16_bf16 v[16:31], v[84:87], v[64:67], v[16:31]
	v_add_f32_e32 v213, v213, v116
	v_add_f32_e32 v213, v213, v117
	v_add_f32_e32 v213, v213, v118
	v_add_f32_e32 v213, v213, v119
	s_waitcnt lgkmcnt(0)
	v_mfma_f32_32x32x16_bf16 v[32:47], v[92:95], v[64:67], v[32:47]
	v_add_f32_e32 v213, v213, v120
	v_add_f32_e32 v213, v213, v121
	v_add_f32_e32 v213, v213, v122
	v_add_f32_e32 v213, v213, v123
	s_setprio 2
	s_waitcnt lgkmcnt(0)
	s_barrier
	ds_read_b128 v[240:243], v195
	ds_read_b128 v[244:247], v195 offset:4608
	ds_read_b128 v[116:119], v195 offset:32
	ds_read_b128 v[120:123], v195 offset:4640
	ds_read_b128 v[124:127], v195 offset:64
	ds_read_b128 v[128:131], v195 offset:4672
	ds_read_b128 v[132:135], v195 offset:96
	ds_read_b128 v[136:139], v195 offset:4704
	v_add_f32_e32 v1, v1, v184
	v_exp_f32_e32 v140, v144
	v_exp_f32_e32 v141, v145
	v_exp_f32_e32 v142, v146
	v_exp_f32_e32 v143, v147
	s_waitcnt lgkmcnt(6)
	v_mfma_f32_32x32x16_bf16 v[80:95], v[240:243], v[180:183], v[48:63]
	v_mfma_f32_32x32x16_bf16 v[64:79], v[244:247], v[180:183], v[48:63]
	v_exp_f32_e32 v144, v148
	v_exp_f32_e32 v145, v149
	v_exp_f32_e32 v146, v150
	v_exp_f32_e32 v147, v151
	s_waitcnt lgkmcnt(5)
	v_mfma_f32_32x32x16_bf16 v[80:95], v[116:119], v[176:179], v[80:95]
	v_exp_f32_e32 v148, v152
	v_exp_f32_e32 v149, v153
	v_exp_f32_e32 v150, v154
	v_exp_f32_e32 v151, v155
	s_waitcnt lgkmcnt(4)
	v_mfma_f32_32x32x16_bf16 v[64:79], v[120:123], v[176:179], v[64:79]
	v_exp_f32_e32 v152, v156
	v_exp_f32_e32 v153, v157
	v_exp_f32_e32 v154, v158
	v_exp_f32_e32 v155, v159
	s_waitcnt lgkmcnt(3)
	v_mfma_f32_32x32x16_bf16 v[80:95], v[124:127], v[172:175], v[80:95]
	v_exp_f32_e32 v156, v96
	v_exp_f32_e32 v157, v97
	v_exp_f32_e32 v158, v98
	v_exp_f32_e32 v159, v99
	s_waitcnt lgkmcnt(2)
	v_mfma_f32_32x32x16_bf16 v[64:79], v[128:131], v[172:175], v[64:79]
	v_exp_f32_e32 v166, v100
	v_exp_f32_e32 v167, v101
	v_exp_f32_e32 v184, v102
	v_exp_f32_e32 v185, v103
	s_waitcnt lgkmcnt(1)
	v_mfma_f32_32x32x16_bf16 v[80:95], v[132:135], v[168:171], v[80:95]
	v_exp_f32_e32 v186, v104
	v_exp_f32_e32 v187, v105
	v_exp_f32_e32 v210, v106
	v_exp_f32_e32 v211, v107
	s_waitcnt lgkmcnt(0)
	v_mfma_f32_32x32x16_bf16 v[64:79], v[136:139], v[168:171], v[64:79]
	v_exp_f32_e32 v212, v108
	v_exp_f32_e32 v214, v109
	v_exp_f32_e32 v215, v110
	v_exp_f32_e32 v216, v111
	v_add_u32_e32 v124, s28, v195
	ds_read_b128 v[240:243], v195 offset:9216
	ds_read_b128 v[244:247], v195 offset:13824
	ds_read_b128 v[96:99], v124 offset:41472
	ds_read_b128 v[100:103], v124 offset:36864
	ds_read_b128 v[104:107], v124 offset:36896
	ds_read_b128 v[108:111], v124 offset:41504
	ds_read_b128 v[112:115], v124 offset:36928
	ds_read_b128 v[116:119], v124 offset:41536
	ds_read_b128 v[120:123], v124 offset:36960
	ds_read_b128 v[124:127], v124 offset:41568
	s_cmp_gt_i32 s26, 2
	s_cselect_b32 s29, -3, 2
	s_add_i32 s29, s29, s26
	s_mulk_i32 s29, 0x2400
	s_waitcnt vmcnt(3)
	ds_write_b128 v208, v[10:13] offset:18432
	v_add_u32_e32 v10, s29, v208
	s_mov_b32 s29, 0x1da90000
	s_waitcnt vmcnt(2)
	ds_write_b128 v10, v[160:163] offset:36864
	s_add_i32 s92, s13, -4
	s_lshl_b32 s92, s92, 13
	s_add_u32 vcc_lo, s100, s92
	s_addc_u32 vcc_hi, s101, 0
	global_load_dwordx4 v[128:131], v248, vcc
	s_lshl_b32 s92, s27, 7
	s_add_u32 vcc_lo, s98, s92
	s_addc_u32 vcc_hi, s99, 0
	global_load_dwordx4 v[10:13], v249, vcc
	v_add_f32_e32 v1, v1, v213
	s_add_i32 s28, s26, 1
	s_setprio 1
	v_cvt_pk_bf16_f32 v132, v140, v141
	v_cvt_pk_bf16_f32 v133, v142, v143
	v_cvt_pk_bf16_f32 v134, v144, v145
	v_cvt_pk_bf16_f32 v135, v146, v147
	s_waitcnt lgkmcnt(8)
	s_nop 0
	v_mfma_f32_32x32x16_bf16 v[16:31], v[100:103], v[132:135], v[16:31]
	v_add_f32_e32 v160, v140, v141
	v_add_f32_e32 v160, v160, v142
	v_add_f32_e32 v160, v160, v143
	s_nop 0
	v_mfma_f32_32x32x16_bf16 v[32:47], v[96:99], v[132:135], v[32:47]
	v_cvt_pk_bf16_f32 v100, v148, v149
	v_cvt_pk_bf16_f32 v101, v150, v151
	v_cvt_pk_bf16_f32 v102, v152, v153
	v_cvt_pk_bf16_f32 v103, v154, v155
	v_add_f32_e32 v160, v160, v144
	v_add_f32_e32 v160, v160, v145
	v_add_f32_e32 v160, v160, v146
	v_add_f32_e32 v160, v160, v147
	s_waitcnt lgkmcnt(7)
	v_mfma_f32_32x32x16_bf16 v[16:31], v[104:107], v[100:103], v[16:31]
	v_add_f32_e32 v160, v160, v148
	v_add_f32_e32 v160, v160, v149
	v_add_f32_e32 v160, v160, v150
	v_add_f32_e32 v160, v160, v151
	s_waitcnt lgkmcnt(6)
	v_mfma_f32_32x32x16_bf16 v[32:47], v[108:111], v[100:103], v[32:47]
	v_cvt_pk_bf16_f32 v96, v156, v157
	v_cvt_pk_bf16_f32 v97, v158, v159
	v_cvt_pk_bf16_f32 v98, v166, v167
	v_cvt_pk_bf16_f32 v99, v184, v185
	v_add_f32_e32 v160, v160, v152
	v_add_f32_e32 v160, v160, v153
	v_add_f32_e32 v160, v160, v154
	v_add_f32_e32 v160, v160, v155
	s_waitcnt lgkmcnt(5)
	v_mfma_f32_32x32x16_bf16 v[16:31], v[112:115], v[96:99], v[16:31]
	v_add_f32_e32 v160, v160, v156
	v_add_f32_e32 v160, v160, v157
	v_add_f32_e32 v160, v160, v158
	v_add_f32_e32 v160, v160, v159
	s_waitcnt lgkmcnt(4)
	v_mfma_f32_32x32x16_bf16 v[32:47], v[116:119], v[96:99], v[32:47]
	v_cvt_pk_bf16_f32 v100, v186, v187
	v_cvt_pk_bf16_f32 v101, v210, v211
	v_cvt_pk_bf16_f32 v102, v212, v214
	v_cvt_pk_bf16_f32 v103, v215, v216
	v_add_f32_e32 v160, v160, v166
	v_add_f32_e32 v160, v160, v167
	v_add_f32_e32 v160, v160, v184
	v_add_f32_e32 v160, v160, v185
	s_waitcnt lgkmcnt(3)
	v_mfma_f32_32x32x16_bf16 v[16:31], v[120:123], v[100:103], v[16:31]
	v_add_f32_e32 v160, v160, v186
	v_add_f32_e32 v160, v160, v187
	v_add_f32_e32 v160, v160, v210
	v_add_f32_e32 v160, v160, v211
	s_waitcnt lgkmcnt(2)
	v_mfma_f32_32x32x16_bf16 v[32:47], v[124:127], v[100:103], v[32:47]
	v_add_f32_e32 v160, v160, v212
	v_add_f32_e32 v160, v160, v214
	v_add_f32_e32 v160, v160, v215
	v_add_f32_e32 v160, v160, v216
	s_setprio 0
	ds_read_b128 v[132:135], v195 offset:9248
	ds_read_b128 v[140:143], v195 offset:13856
	ds_read_b128 v[144:147], v195 offset:9280
	ds_read_b128 v[148:151], v195 offset:9312
	ds_read_b128 v[152:155], v195 offset:13888
	ds_read_b128 v[156:159], v195 offset:13920
	s_cmp_lg_u32 s26, 4
	s_cselect_b32 s26, s28, 0
	s_waitcnt lgkmcnt(6)
	v_mfma_f32_32x32x16_bf16 v[112:127], v[240:243], v[180:183], v[48:63]
	v_exp_f32_e32 v161, v80
	v_exp_f32_e32 v162, v81
	v_exp_f32_e32 v163, v82
	v_exp_f32_e32 v164, v83
	s_waitcnt lgkmcnt(5)
	v_mfma_f32_32x32x16_bf16 v[96:111], v[244:247], v[180:183], v[48:63]
	v_exp_f32_e32 v165, v84
	v_exp_f32_e32 v166, v85
	v_exp_f32_e32 v167, v86
	v_exp_f32_e32 v184, v87
	v_mfma_f32_32x32x16_bf16 v[112:127], v[132:135], v[176:179], v[112:127]
	v_exp_f32_e32 v136, v88
	v_exp_f32_e32 v137, v89
	v_exp_f32_e32 v138, v90
	v_exp_f32_e32 v139, v91
	s_waitcnt lgkmcnt(4)
	v_mfma_f32_32x32x16_bf16 v[96:111], v[140:143], v[176:179], v[96:111]
	v_exp_f32_e32 v185, v92
	v_exp_f32_e32 v186, v93
	v_exp_f32_e32 v187, v94
	v_exp_f32_e32 v210, v95
	s_waitcnt lgkmcnt(3)
	v_mfma_f32_32x32x16_bf16 v[112:127], v[144:147], v[172:175], v[112:127]
	v_exp_f32_e32 v140, v64
	v_exp_f32_e32 v141, v65
	v_exp_f32_e32 v142, v66
	v_exp_f32_e32 v143, v67
	s_waitcnt lgkmcnt(1)
	v_mfma_f32_32x32x16_bf16 v[96:111], v[152:155], v[172:175], v[96:111]
	v_exp_f32_e32 v144, v68
	v_exp_f32_e32 v145, v69
	v_exp_f32_e32 v146, v70
	v_exp_f32_e32 v147, v71
	v_mfma_f32_32x32x16_bf16 v[112:127], v[148:151], v[168:171], v[112:127]
	v_exp_f32_e32 v152, v72
	v_exp_f32_e32 v153, v73
	v_exp_f32_e32 v154, v74
	v_exp_f32_e32 v155, v75
	s_waitcnt lgkmcnt(0)
	v_mfma_f32_32x32x16_bf16 v[96:111], v[156:159], v[168:171], v[96:111]
	v_exp_f32_e32 v148, v76
	v_exp_f32_e32 v149, v77
	v_exp_f32_e32 v150, v78
	v_exp_f32_e32 v151, v79
	s_cmp_gt_i32 s26, 2
	s_cselect_b32 s27, -3, 2
	s_add_i32 s27, s27, s26
	s_mulk_i32 s27, 0x2400
	s_waitcnt vmcnt(3)
	ds_write_b128 v208, v[6:9] offset:27648
	v_add_u32_e32 v6, s27, v208
	s_add_i32 s27, s26, 1
	s_cmp_lg_u32 s26, 4
	s_cselect_b32 s27, s27, 0
	s_add_i32 s26, s13, -3
	s_min_u32 s28, s26, s12
	s_lshl_b32 s92, s28, 13
	s_waitcnt vmcnt(2)
	ds_write_b128 v6, v[2:5] offset:36864
	s_mul_i32 vcc_lo, s27, 0x2400
	s_add_i32 vcc_lo, vcc_lo, 0xffffdc00
	s_cmp_lg_u32 s27, 0
	s_cselect_b32 vcc_lo, vcc_lo, 0x9000
	v_add_u32_e32 v14, vcc_lo, v195
	ds_read_b128 v[64:67], v14 offset:36864
	ds_read_b128 v[68:71], v14 offset:36896
	ds_read_b128 v[72:75], v14 offset:41472
	ds_read_b128 v[76:79], v14 offset:41504
	ds_read_b128 v[80:83], v14 offset:36928
	ds_read_b128 v[84:87], v14 offset:36960
	ds_read_b128 v[88:91], v14 offset:41536
	ds_read_b128 v[92:95], v14 offset:41568
	s_add_u32 vcc_lo, s100, s92
	s_addc_u32 vcc_hi, s101, 0
	global_load_dwordx4 v[6:9], v248, vcc
	s_nop 0
	s_add_i32 s92, s13, -4
	s_lshl_b32 s92, s92, 7
	s_add_u32 vcc_lo, s98, s92
	s_addc_u32 vcc_hi, s99, 0
	global_load_dwordx4 v[2:5], v249, vcc
	s_mul_i32 s29, s27, 0x2400
	s_setprio 3
	v_cvt_pk_bf16_f32 v132, v161, v162
	v_cvt_pk_bf16_f32 v133, v163, v164
	v_cvt_pk_bf16_f32 v134, v165, v166
	v_cvt_pk_bf16_f32 v135, v167, v184
	s_waitcnt lgkmcnt(7)
	s_nop 0
	v_mfma_f32_32x32x16_bf16 v[16:31], v[64:67], v[132:135], v[16:31]
	v_add_f32_e32 v14, v161, v162
	v_add_f32_e32 v14, v14, v163
	v_add_f32_e32 v14, v14, v164
	s_waitcnt lgkmcnt(5)
	v_mfma_f32_32x32x16_bf16 v[32:47], v[72:75], v[132:135], v[32:47]
	v_cvt_pk_bf16_f32 v64, v136, v137
	v_cvt_pk_bf16_f32 v65, v138, v139
	v_cvt_pk_bf16_f32 v66, v185, v186
	v_cvt_pk_bf16_f32 v67, v187, v210
	v_add_f32_e32 v14, v14, v165
	v_add_f32_e32 v14, v14, v166
	v_add_f32_e32 v14, v14, v167
	v_add_f32_e32 v14, v14, v184
	s_nop 0
	v_mfma_f32_32x32x16_bf16 v[16:31], v[68:71], v[64:67], v[16:31]
	v_add_f32_e32 v14, v14, v136
	v_add_f32_e32 v14, v14, v137
	v_add_f32_e32 v14, v14, v138
	v_add_f32_e32 v14, v14, v139
	s_waitcnt lgkmcnt(4)
	v_mfma_f32_32x32x16_bf16 v[32:47], v[76:79], v[64:67], v[32:47]
	v_cvt_pk_bf16_f32 v68, v140, v141
	v_cvt_pk_bf16_f32 v69, v142, v143
	v_cvt_pk_bf16_f32 v70, v144, v145
	v_cvt_pk_bf16_f32 v71, v146, v147
	v_add_f32_e32 v14, v14, v185
	v_add_f32_e32 v14, v14, v186
	v_add_f32_e32 v14, v14, v187
	v_add_f32_e32 v14, v14, v210
	s_waitcnt lgkmcnt(3)
	v_mfma_f32_32x32x16_bf16 v[16:31], v[80:83], v[68:71], v[16:31]
	v_add_f32_e32 v14, v14, v140
	v_add_f32_e32 v14, v14, v141
	v_add_f32_e32 v14, v14, v142
	v_add_f32_e32 v14, v14, v143
	s_waitcnt lgkmcnt(1)
	v_mfma_f32_32x32x16_bf16 v[32:47], v[88:91], v[68:71], v[32:47]
	v_cvt_pk_bf16_f32 v64, v152, v153
	v_cvt_pk_bf16_f32 v65, v154, v155
	v_cvt_pk_bf16_f32 v66, v148, v149
	v_cvt_pk_bf16_f32 v67, v150, v151
	v_add_f32_e32 v14, v14, v144
	v_add_f32_e32 v14, v14, v145
	v_add_f32_e32 v14, v14, v146
	v_add_f32_e32 v14, v14, v147
	s_nop 0
	v_mfma_f32_32x32x16_bf16 v[16:31], v[84:87], v[64:67], v[16:31]
	v_add_f32_e32 v14, v14, v152
	v_add_f32_e32 v14, v14, v153
	v_add_f32_e32 v14, v14, v154
	v_add_f32_e32 v14, v14, v155
	s_waitcnt lgkmcnt(0)
	v_mfma_f32_32x32x16_bf16 v[32:47], v[92:95], v[64:67], v[32:47]
	v_add_f32_e32 v14, v14, v148
	v_add_f32_e32 v14, v14, v149
	v_add_f32_e32 v14, v14, v150
	v_add_f32_e32 v14, v14, v151
	s_setprio 2
	s_waitcnt lgkmcnt(0)
	s_barrier
	ds_read_b128 v[240:243], v195 offset:18432
	ds_read_b128 v[244:247], v195 offset:23040
	ds_read_b128 v[136:139], v195 offset:18464
	ds_read_b128 v[140:143], v195 offset:23072
	ds_read_b128 v[144:147], v195 offset:18496
	ds_read_b128 v[148:151], v195 offset:23104
	ds_read_b128 v[152:155], v195 offset:18528
	ds_read_b128 v[156:159], v195 offset:23136
	v_add_f32_e32 v1, v1, v160
	v_exp_f32_e32 v160, v112
	v_exp_f32_e32 v161, v113
	v_exp_f32_e32 v162, v114
	v_exp_f32_e32 v163, v115
	s_waitcnt lgkmcnt(6)
	v_mfma_f32_32x32x16_bf16 v[80:95], v[240:243], v[180:183], v[48:63]
	v_mfma_f32_32x32x16_bf16 v[64:79], v[244:247], v[180:183], v[48:63]
	v_exp_f32_e32 v164, v116
	v_exp_f32_e32 v165, v117
	v_exp_f32_e32 v166, v118
	v_exp_f32_e32 v167, v119
	s_waitcnt lgkmcnt(5)
	v_mfma_f32_32x32x16_bf16 v[80:95], v[136:139], v[176:179], v[80:95]
	v_exp_f32_e32 v184, v120
	v_exp_f32_e32 v185, v121
	v_exp_f32_e32 v186, v122
	v_exp_f32_e32 v187, v123
	s_waitcnt lgkmcnt(4)
	v_mfma_f32_32x32x16_bf16 v[64:79], v[140:143], v[176:179], v[64:79]
	v_exp_f32_e32 v136, v124
	v_exp_f32_e32 v137, v125
	v_exp_f32_e32 v138, v126
	v_exp_f32_e32 v139, v127
	s_waitcnt lgkmcnt(3)
	v_mfma_f32_32x32x16_bf16 v[80:95], v[144:147], v[172:175], v[80:95]
	v_exp_f32_e32 v140, v96
	v_exp_f32_e32 v141, v97
	v_exp_f32_e32 v142, v98
	v_exp_f32_e32 v143, v99
	s_waitcnt lgkmcnt(2)
	v_mfma_f32_32x32x16_bf16 v[64:79], v[148:151], v[172:175], v[64:79]
	v_exp_f32_e32 v144, v100
	v_exp_f32_e32 v145, v101
	v_exp_f32_e32 v146, v102
	v_exp_f32_e32 v147, v103
	s_waitcnt lgkmcnt(1)
	v_mfma_f32_32x32x16_bf16 v[80:95], v[152:155], v[168:171], v[80:95]
	v_exp_f32_e32 v148, v104
	v_exp_f32_e32 v149, v105
	v_exp_f32_e32 v150, v106
	v_exp_f32_e32 v151, v107
	s_waitcnt lgkmcnt(0)
	v_mfma_f32_32x32x16_bf16 v[64:79], v[156:159], v[168:171], v[64:79]
	v_exp_f32_e32 v152, v108
	v_exp_f32_e32 v153, v109
	v_exp_f32_e32 v154, v110
	v_exp_f32_e32 v155, v111
	s_cmp_gt_i32 s27, 2
	s_cselect_b32 s34, -3, 2
	s_waitcnt vmcnt(3)
	ds_write_b128 v208, v[128:131]
	v_add_u32_e32 v128, s29, v195
	ds_read_b128 v[240:243], v195 offset:27648
	ds_read_b128 v[244:247], v195 offset:32256
	ds_read_b128 v[96:99], v128 offset:41472
	ds_read_b128 v[100:103], v128 offset:36864
	ds_read_b128 v[104:107], v128 offset:36896
	ds_read_b128 v[108:111], v128 offset:41504
	ds_read_b128 v[116:119], v128 offset:36928
	ds_read_b128 v[120:123], v128 offset:41536
	ds_read_b128 v[124:127], v128 offset:36960
	ds_read_b128 v[128:131], v128 offset:41568
	s_add_i32 s34, s34, s27
	s_add_i32 s29, s13, -2
	s_mulk_i32 s34, 0x2400
	s_min_u32 s29, s29, s12
	v_add_u32_e32 v15, s34, v208
	s_lshl_b32 s92, s29, 13
	s_waitcnt vmcnt(2)
	ds_write_b128 v15, v[10:13] offset:36864
	s_add_u32 vcc_lo, s100, s92
	s_addc_u32 vcc_hi, s101, 0
	global_load_dwordx4 v[10:13], v248, vcc
	s_lshl_b32 s92, s28, 7
	v_add_f32_e32 v1, v1, v14
	s_add_u32 vcc_lo, s98, s92
	s_addc_u32 vcc_hi, s99, 0
	global_load_dwordx4 v[112:115], v249, vcc
	s_add_i32 s34, s27, 1
	s_setprio 1
	v_cvt_pk_bf16_f32 v132, v160, v161
	v_cvt_pk_bf16_f32 v133, v162, v163
	v_cvt_pk_bf16_f32 v134, v164, v165
	v_cvt_pk_bf16_f32 v135, v166, v167
	s_waitcnt lgkmcnt(7)
	s_nop 0
	v_mfma_f32_32x32x16_bf16 v[16:31], v[100:103], v[132:135], v[16:31]
	v_add_f32_e32 v14, v160, v161
	v_add_f32_e32 v14, v14, v162
	v_add_f32_e32 v14, v14, v163
	s_nop 0
	v_mfma_f32_32x32x16_bf16 v[32:47], v[96:99], v[132:135], v[32:47]
	v_cvt_pk_bf16_f32 v100, v184, v185
	v_cvt_pk_bf16_f32 v101, v186, v187
	v_cvt_pk_bf16_f32 v102, v136, v137
	v_cvt_pk_bf16_f32 v103, v138, v139
	v_add_f32_e32 v14, v14, v164
	v_add_f32_e32 v14, v14, v165
	v_add_f32_e32 v14, v14, v166
	v_add_f32_e32 v14, v14, v167
	s_waitcnt lgkmcnt(6)
	v_mfma_f32_32x32x16_bf16 v[16:31], v[104:107], v[100:103], v[16:31]
	v_add_f32_e32 v14, v14, v184
	v_add_f32_e32 v14, v14, v185
	v_add_f32_e32 v14, v14, v186
	v_add_f32_e32 v14, v14, v187
	s_waitcnt lgkmcnt(5)
	v_mfma_f32_32x32x16_bf16 v[32:47], v[108:111], v[100:103], v[32:47]
	v_cvt_pk_bf16_f32 v96, v140, v141
	v_cvt_pk_bf16_f32 v97, v142, v143
	v_cvt_pk_bf16_f32 v98, v144, v145
	v_cvt_pk_bf16_f32 v99, v146, v147
	v_add_f32_e32 v14, v14, v136
	v_add_f32_e32 v14, v14, v137
	v_add_f32_e32 v14, v14, v138
	v_add_f32_e32 v14, v14, v139
	s_waitcnt lgkmcnt(4)
	v_mfma_f32_32x32x16_bf16 v[16:31], v[116:119], v[96:99], v[16:31]
	v_add_f32_e32 v14, v14, v140
	v_add_f32_e32 v14, v14, v141
	v_add_f32_e32 v14, v14, v142
	v_add_f32_e32 v14, v14, v143
	s_waitcnt lgkmcnt(3)
	v_mfma_f32_32x32x16_bf16 v[32:47], v[120:123], v[96:99], v[32:47]
	v_cvt_pk_bf16_f32 v100, v148, v149
	v_cvt_pk_bf16_f32 v101, v150, v151
	v_cvt_pk_bf16_f32 v102, v152, v153
	v_cvt_pk_bf16_f32 v103, v154, v155
	v_add_f32_e32 v14, v14, v144
	v_add_f32_e32 v14, v14, v145
	v_add_f32_e32 v14, v14, v146
	v_add_f32_e32 v14, v14, v147
	s_waitcnt lgkmcnt(2)
	v_mfma_f32_32x32x16_bf16 v[16:31], v[124:127], v[100:103], v[16:31]
	v_add_f32_e32 v14, v14, v148
	v_add_f32_e32 v14, v14, v149
	v_add_f32_e32 v14, v14, v150
	v_add_f32_e32 v14, v14, v151
	s_waitcnt lgkmcnt(1)
	v_mfma_f32_32x32x16_bf16 v[32:47], v[128:131], v[100:103], v[32:47]
	v_add_f32_e32 v14, v14, v152
	v_add_f32_e32 v14, v14, v153
	v_add_f32_e32 v14, v14, v154
	v_add_f32_e32 v14, v14, v155
	s_setprio 0
	ds_read_b128 v[116:119], v195 offset:27680
	ds_read_b128 v[124:127], v195 offset:32288
	ds_read_b128 v[128:131], v195 offset:27712
	ds_read_b128 v[132:135], v195 offset:27744
	ds_read_b128 v[136:139], v195 offset:32320
	ds_read_b128 v[140:143], v195 offset:32352
	s_cmp_lg_u32 s27, 4
	s_cselect_b32 s27, s34, 0
	s_waitcnt lgkmcnt(6)
	v_mfma_f32_32x32x16_bf16 v[152:167], v[240:243], v[180:183], v[48:63]
	v_exp_f32_e32 v15, v80
	v_exp_f32_e32 v144, v81
	v_exp_f32_e32 v145, v82
	v_exp_f32_e32 v146, v83
	s_waitcnt lgkmcnt(5)
	v_mfma_f32_32x32x16_bf16 v[96:111], v[244:247], v[180:183], v[48:63]
	v_exp_f32_e32 v147, v84
	v_exp_f32_e32 v148, v85
	v_exp_f32_e32 v149, v86
	v_exp_f32_e32 v150, v87
	v_mfma_f32_32x32x16_bf16 v[152:167], v[116:119], v[176:179], v[152:167]
	v_exp_f32_e32 v120, v88
	v_exp_f32_e32 v121, v89
	v_exp_f32_e32 v122, v90
	v_exp_f32_e32 v123, v91
	s_waitcnt lgkmcnt(4)
	v_mfma_f32_32x32x16_bf16 v[96:111], v[124:127], v[176:179], v[96:111]
	v_exp_f32_e32 v151, v92
	v_exp_f32_e32 v184, v93
	v_exp_f32_e32 v185, v94
	v_exp_f32_e32 v186, v95
	s_waitcnt lgkmcnt(3)
	v_mfma_f32_32x32x16_bf16 v[152:167], v[128:131], v[172:175], v[152:167]
	v_exp_f32_e32 v124, v64
	v_exp_f32_e32 v125, v65
	v_exp_f32_e32 v126, v66
	v_exp_f32_e32 v127, v67
	s_waitcnt lgkmcnt(1)
	v_mfma_f32_32x32x16_bf16 v[96:111], v[136:139], v[172:175], v[96:111]
	v_exp_f32_e32 v128, v68
	v_exp_f32_e32 v129, v69
	v_exp_f32_e32 v130, v70
	v_exp_f32_e32 v131, v71
	v_mfma_f32_32x32x16_bf16 v[152:167], v[132:135], v[168:171], v[152:167]
	v_exp_f32_e32 v136, v72
	v_exp_f32_e32 v137, v73
	v_exp_f32_e32 v138, v74
	v_exp_f32_e32 v139, v75
	s_waitcnt lgkmcnt(0)
	v_mfma_f32_32x32x16_bf16 v[96:111], v[140:143], v[168:171], v[96:111]
	v_exp_f32_e32 v132, v76
	v_exp_f32_e32 v133, v77
	v_exp_f32_e32 v134, v78
	v_exp_f32_e32 v135, v79
	s_cmp_gt_i32 s27, 2
	s_cselect_b32 s28, -3, 2
	s_add_i32 s28, s28, s27
	s_mulk_i32 s28, 0x2400
	s_waitcnt vmcnt(3)
	ds_write_b128 v208, v[6:9] offset:9216
	v_add_u32_e32 v6, s28, v208
	s_add_i32 s28, s27, 1
	s_cmp_lg_u32 s27, 4
	s_cselect_b32 s27, s28, 0
	s_add_i32 s28, s13, -1
	s_min_u32 s28, s28, s12
	s_lshl_b32 s92, s28, 13
	s_waitcnt vmcnt(2)
	ds_write_b128 v6, v[2:5] offset:36864
	s_mul_i32 vcc_lo, s27, 0x2400
	s_add_i32 vcc_lo, vcc_lo, 0xffffdc00
	s_cmp_lg_u32 s27, 0
	s_cselect_b32 vcc_lo, vcc_lo, 0x9000
	v_add_u32_e32 v92, vcc_lo, v195
	ds_read_b128 v[64:67], v92 offset:36864
	ds_read_b128 v[68:71], v92 offset:36896
	ds_read_b128 v[72:75], v92 offset:41472
	ds_read_b128 v[76:79], v92 offset:41504
	ds_read_b128 v[80:83], v92 offset:36928
	ds_read_b128 v[84:87], v92 offset:36960
	ds_read_b128 v[88:91], v92 offset:41536
	ds_read_b128 v[92:95], v92 offset:41568
	s_add_u32 vcc_lo, s100, s92
	s_addc_u32 vcc_hi, s101, 0
	global_load_dwordx4 v[6:9], v248, vcc
	s_lshl_b32 s92, s29, 7
	s_add_u32 vcc_lo, s98, s92
	s_addc_u32 vcc_hi, s99, 0
	global_load_dwordx4 v[2:5], v249, vcc
	s_nop 0
	s_mul_i32 s29, s27, 0x2400
	s_setprio 3
	v_cvt_pk_bf16_f32 v116, v15, v144
	v_cvt_pk_bf16_f32 v117, v145, v146
	v_cvt_pk_bf16_f32 v118, v147, v148
	v_cvt_pk_bf16_f32 v119, v149, v150
	s_waitcnt lgkmcnt(7)
	s_nop 0
	v_mfma_f32_32x32x16_bf16 v[16:31], v[64:67], v[116:119], v[16:31]
	v_add_f32_e32 v187, v15, v144
	v_add_f32_e32 v187, v187, v145
	v_add_f32_e32 v187, v187, v146
	s_waitcnt lgkmcnt(5)
	v_mfma_f32_32x32x16_bf16 v[32:47], v[72:75], v[116:119], v[32:47]
	v_cvt_pk_bf16_f32 v64, v120, v121
	v_cvt_pk_bf16_f32 v65, v122, v123
	v_cvt_pk_bf16_f32 v66, v151, v184
	v_cvt_pk_bf16_f32 v67, v185, v186
	v_add_f32_e32 v187, v187, v147
	v_add_f32_e32 v187, v187, v148
	v_add_f32_e32 v187, v187, v149
	v_add_f32_e32 v187, v187, v150
	s_nop 0
	v_mfma_f32_32x32x16_bf16 v[16:31], v[68:71], v[64:67], v[16:31]
	v_add_f32_e32 v187, v187, v120
	v_add_f32_e32 v187, v187, v121
	v_add_f32_e32 v187, v187, v122
	v_add_f32_e32 v187, v187, v123
	s_waitcnt lgkmcnt(4)
	v_mfma_f32_32x32x16_bf16 v[32:47], v[76:79], v[64:67], v[32:47]
	v_cvt_pk_bf16_f32 v68, v124, v125
	v_cvt_pk_bf16_f32 v69, v126, v127
	v_cvt_pk_bf16_f32 v70, v128, v129
	v_cvt_pk_bf16_f32 v71, v130, v131
	v_add_f32_e32 v187, v187, v151
	v_add_f32_e32 v187, v187, v184
	v_add_f32_e32 v187, v187, v185
	v_add_f32_e32 v187, v187, v186
	s_waitcnt lgkmcnt(3)
	v_mfma_f32_32x32x16_bf16 v[16:31], v[80:83], v[68:71], v[16:31]
	v_add_f32_e32 v187, v187, v124
	v_add_f32_e32 v187, v187, v125
	v_add_f32_e32 v187, v187, v126
	v_add_f32_e32 v187, v187, v127
	s_waitcnt lgkmcnt(1)
	v_mfma_f32_32x32x16_bf16 v[32:47], v[88:91], v[68:71], v[32:47]
	v_cvt_pk_bf16_f32 v64, v136, v137
	v_cvt_pk_bf16_f32 v65, v138, v139
	v_cvt_pk_bf16_f32 v66, v132, v133
	v_cvt_pk_bf16_f32 v67, v134, v135
	v_add_f32_e32 v187, v187, v128
	v_add_f32_e32 v187, v187, v129
	v_add_f32_e32 v187, v187, v130
	v_add_f32_e32 v187, v187, v131
	s_nop 0
	v_mfma_f32_32x32x16_bf16 v[16:31], v[84:87], v[64:67], v[16:31]
	v_add_f32_e32 v187, v187, v136
	v_add_f32_e32 v187, v187, v137
	v_add_f32_e32 v187, v187, v138
	v_add_f32_e32 v187, v187, v139
	s_waitcnt lgkmcnt(0)
	v_mfma_f32_32x32x16_bf16 v[32:47], v[92:95], v[64:67], v[32:47]
	v_add_f32_e32 v187, v187, v132
	v_add_f32_e32 v187, v187, v133
	v_add_f32_e32 v187, v187, v134
	v_add_f32_e32 v187, v187, v135
	s_setprio 2
	s_waitcnt lgkmcnt(0)
	s_barrier
	ds_read_b128 v[240:243], v195
	ds_read_b128 v[244:247], v195 offset:4608
	ds_read_b128 v[72:75], v195 offset:32
	ds_read_b128 v[76:79], v195 offset:4640
	ds_read_b128 v[80:83], v195 offset:64
	ds_read_b128 v[84:87], v195 offset:4672
	ds_read_b128 v[88:91], v195 offset:96
	ds_read_b128 v[92:95], v195 offset:4704
	v_add_f32_e32 v1, v1, v14
	v_exp_f32_e32 v14, v152
	v_exp_f32_e32 v15, v153
	v_exp_f32_e32 v116, v154
	v_exp_f32_e32 v117, v155
	s_waitcnt lgkmcnt(6)
	v_mfma_f32_32x32x16_bf16 v[136:151], v[240:243], v[180:183], v[48:63]
	v_mfma_f32_32x32x16_bf16 v[120:135], v[244:247], v[180:183], v[48:63]
	v_exp_f32_e32 v118, v156
	v_exp_f32_e32 v119, v157
	v_exp_f32_e32 v184, v158
	v_exp_f32_e32 v185, v159
	s_waitcnt lgkmcnt(5)
	v_mfma_f32_32x32x16_bf16 v[136:151], v[72:75], v[176:179], v[136:151]
	v_exp_f32_e32 v186, v160
	v_exp_f32_e32 v210, v161
	v_exp_f32_e32 v211, v162
	v_exp_f32_e32 v212, v163
	s_waitcnt lgkmcnt(4)
	v_mfma_f32_32x32x16_bf16 v[120:135], v[76:79], v[176:179], v[120:135]
	v_exp_f32_e32 v160, v164
	v_exp_f32_e32 v161, v165
	v_exp_f32_e32 v162, v166
	v_exp_f32_e32 v163, v167
	s_waitcnt lgkmcnt(3)
	v_mfma_f32_32x32x16_bf16 v[136:151], v[80:83], v[172:175], v[136:151]
	v_exp_f32_e32 v164, v96
	v_exp_f32_e32 v165, v97
	v_exp_f32_e32 v166, v98
	v_exp_f32_e32 v167, v99
	s_waitcnt lgkmcnt(2)
	v_mfma_f32_32x32x16_bf16 v[120:135], v[84:87], v[172:175], v[120:135]
	v_exp_f32_e32 v96, v100
	v_exp_f32_e32 v97, v101
	v_exp_f32_e32 v98, v102
	v_exp_f32_e32 v99, v103
	s_waitcnt lgkmcnt(1)
	v_mfma_f32_32x32x16_bf16 v[136:151], v[88:91], v[168:171], v[136:151]
	v_exp_f32_e32 v100, v104
	v_exp_f32_e32 v101, v105
	v_exp_f32_e32 v102, v106
	v_exp_f32_e32 v103, v107
	s_waitcnt lgkmcnt(0)
	v_mfma_f32_32x32x16_bf16 v[120:135], v[92:95], v[168:171], v[120:135]
	v_exp_f32_e32 v104, v108
	v_exp_f32_e32 v105, v109
	v_exp_f32_e32 v106, v110
	v_exp_f32_e32 v107, v111
	s_cmp_gt_i32 s27, 2
	s_cselect_b32 s34, -3, 2
	s_add_i32 s34, s34, s27
	s_mulk_i32 s34, 0x2400
	v_add_u32_e32 v88, s29, v195
	s_min_u32 s29, s13, s12
	s_waitcnt vmcnt(3)
	ds_write_b128 v208, v[10:13] offset:18432
	v_add_u32_e32 v10, s34, v208
	s_lshl_b32 s92, s29, 13
	s_waitcnt vmcnt(2)
	ds_write_b128 v10, v[112:115] offset:36864
	ds_read_b128 v[240:243], v195 offset:9216
	ds_read_b128 v[244:247], v195 offset:13824
	ds_read_b128 v[10:13], v88 offset:41472
	ds_read_b128 v[64:67], v88 offset:36864
	ds_read_b128 v[68:71], v88 offset:36896
	ds_read_b128 v[72:75], v88 offset:41504
	ds_read_b128 v[76:79], v88 offset:36928
	ds_read_b128 v[80:83], v88 offset:41536
	ds_read_b128 v[84:87], v88 offset:36960
	ds_read_b128 v[88:91], v88 offset:41568
	s_add_u32 vcc_lo, s100, s92
	s_addc_u32 vcc_hi, s101, 0
	global_load_dwordx4 v[152:155], v248, vcc
	s_lshl_b32 s92, s28, 7
	s_add_u32 vcc_lo, s98, s92
	s_addc_u32 vcc_hi, s99, 0
	global_load_dwordx4 v[156:159], v249, vcc
	v_add_f32_e32 v1, v1, v187
	s_setprio 1
	v_mov_b32_e32 v109, v136
	v_cvt_pk_bf16_f32 v92, v14, v15
	v_cvt_pk_bf16_f32 v93, v116, v117
	v_cvt_pk_bf16_f32 v94, v118, v119
	v_cvt_pk_bf16_f32 v95, v184, v185
	s_waitcnt lgkmcnt(6)
	s_nop 0
	v_mfma_f32_32x32x16_bf16 v[16:31], v[64:67], v[92:95], v[16:31]
	v_max3_f32 v109, v109, v137, v138
	v_max3_f32 v109, v109, v139, v140
	v_add_f32_e32 v108, v14, v15
	v_add_f32_e32 v108, v108, v116
	v_add_f32_e32 v108, v108, v117
	s_nop 0
	v_mfma_f32_32x32x16_bf16 v[32:47], v[10:13], v[92:95], v[32:47]
	v_cvt_pk_bf16_f32 v64, v186, v210
	v_cvt_pk_bf16_f32 v65, v211, v212
	v_cvt_pk_bf16_f32 v66, v160, v161
	v_cvt_pk_bf16_f32 v67, v162, v163
	v_max3_f32 v109, v109, v141, v142
	v_max3_f32 v109, v109, v143, v144
	v_add_f32_e32 v108, v108, v118
	v_add_f32_e32 v108, v108, v119
	v_add_f32_e32 v108, v108, v184
	v_add_f32_e32 v108, v108, v185
	s_waitcnt lgkmcnt(5)
	v_mfma_f32_32x32x16_bf16 v[16:31], v[68:71], v[64:67], v[16:31]
	v_max3_f32 v109, v109, v145, v146
	v_max3_f32 v109, v109, v147, v148
	v_add_f32_e32 v108, v108, v186
	v_add_f32_e32 v108, v108, v210
	v_add_f32_e32 v108, v108, v211
	v_add_f32_e32 v108, v108, v212
	s_waitcnt lgkmcnt(4)
	v_mfma_f32_32x32x16_bf16 v[32:47], v[72:75], v[64:67], v[32:47]
	v_cvt_pk_bf16_f32 v10, v164, v165
	v_cvt_pk_bf16_f32 v11, v166, v167
	v_cvt_pk_bf16_f32 v12, v96, v97
	v_cvt_pk_bf16_f32 v13, v98, v99
	v_max3_f32 v109, v109, v149, v150
	v_max3_f32 v109, v109, v151, v120
	v_add_f32_e32 v108, v108, v160
	v_add_f32_e32 v108, v108, v161
	v_add_f32_e32 v108, v108, v162
	v_add_f32_e32 v108, v108, v163
	s_waitcnt lgkmcnt(3)
	v_mfma_f32_32x32x16_bf16 v[16:31], v[76:79], v[10:13], v[16:31]
	v_max3_f32 v109, v109, v121, v122
	v_max3_f32 v109, v109, v123, v124
	v_add_f32_e32 v108, v108, v164
	v_add_f32_e32 v108, v108, v165
	v_add_f32_e32 v108, v108, v166
	v_add_f32_e32 v108, v108, v167
	s_waitcnt lgkmcnt(2)
	v_mfma_f32_32x32x16_bf16 v[32:47], v[80:83], v[10:13], v[32:47]
	v_cvt_pk_bf16_f32 v64, v100, v101
	v_cvt_pk_bf16_f32 v65, v102, v103
	v_cvt_pk_bf16_f32 v66, v104, v105
	v_cvt_pk_bf16_f32 v67, v106, v107
	v_max3_f32 v109, v109, v125, v126
	v_max3_f32 v109, v109, v127, v128
	v_add_f32_e32 v108, v108, v96
	v_add_f32_e32 v108, v108, v97
	v_add_f32_e32 v108, v108, v98
	v_add_f32_e32 v108, v108, v99
	s_waitcnt lgkmcnt(1)
	v_mfma_f32_32x32x16_bf16 v[16:31], v[84:87], v[64:67], v[16:31]
	v_max3_f32 v109, v109, v129, v130
	v_max3_f32 v109, v109, v131, v132
	v_add_f32_e32 v108, v108, v100
	v_add_f32_e32 v108, v108, v101
	v_add_f32_e32 v108, v108, v102
	v_add_f32_e32 v108, v108, v103
	s_waitcnt lgkmcnt(0)
	v_mfma_f32_32x32x16_bf16 v[32:47], v[88:91], v[64:67], v[32:47]
	v_max3_f32 v109, v109, v133, v134
	v_max3_f32 v109, v109, v135, v135
	v_add_f32_e32 v108, v108, v104
	v_add_f32_e32 v108, v108, v105
	v_add_f32_e32 v108, v108, v106
	v_add_f32_e32 v108, v108, v107
	s_setprio 0
	ds_read_b128 v[164:167], v195 offset:9248
	ds_read_b128 v[160:163], v195 offset:13856
	ds_read_b128 v[74:77], v195 offset:9280
	ds_read_b128 v[66:69], v195 offset:9312
	ds_read_b128 v[70:73], v195 offset:13888
	ds_read_b128 v[10:13], v195 offset:13920
	v_add_f32_e32 v64, v1, v108
	v_mov_b32_e32 v1, v109
	s_nop 1
	v_permlane32_swap_b32_e32 v109, v1
	v_max_f32_e32 v1, v1, v1
	v_max_f32_e32 v14, v109, v109
	v_max_f32_e32 v1, v14, v1
	v_cmp_lt_f32_e32 vcc, s52, v1
	s_cbranch_vccz .LBB0_663
	v_max_f32_e32 v1, v1, v1
	v_max_f32_e32 v14, 0, v1
	v_add_f32_e32 v209, v209, v14
	v_xor_b32_e32 v48, 0x80000000, v209
	v_pk_add_f32 v[136:137], v[136:137], v[14:15] op_sel_hi:[1,0] neg_lo:[0,1] neg_hi:[0,1]
	v_pk_add_f32 v[120:121], v[120:121], v[14:15] op_sel_hi:[1,0] neg_lo:[0,1] neg_hi:[0,1]
	v_pk_add_f32 v[138:139], v[138:139], v[14:15] op_sel_hi:[1,0] neg_lo:[0,1] neg_hi:[0,1]
	v_pk_add_f32 v[122:123], v[122:123], v[14:15] op_sel_hi:[1,0] neg_lo:[0,1] neg_hi:[0,1]
	v_pk_add_f32 v[140:141], v[140:141], v[14:15] op_sel_hi:[1,0] neg_lo:[0,1] neg_hi:[0,1]
	v_pk_add_f32 v[124:125], v[124:125], v[14:15] op_sel_hi:[1,0] neg_lo:[0,1] neg_hi:[0,1]
	v_pk_add_f32 v[142:143], v[142:143], v[14:15] op_sel_hi:[1,0] neg_lo:[0,1] neg_hi:[0,1]
	v_pk_add_f32 v[126:127], v[126:127], v[14:15] op_sel_hi:[1,0] neg_lo:[0,1] neg_hi:[0,1]
	v_pk_add_f32 v[144:145], v[144:145], v[14:15] op_sel_hi:[1,0] neg_lo:[0,1] neg_hi:[0,1]
	v_pk_add_f32 v[128:129], v[128:129], v[14:15] op_sel_hi:[1,0] neg_lo:[0,1] neg_hi:[0,1]
	v_pk_add_f32 v[146:147], v[146:147], v[14:15] op_sel_hi:[1,0] neg_lo:[0,1] neg_hi:[0,1]
	v_pk_add_f32 v[130:131], v[130:131], v[14:15] op_sel_hi:[1,0] neg_lo:[0,1] neg_hi:[0,1]
	v_pk_add_f32 v[148:149], v[148:149], v[14:15] op_sel_hi:[1,0] neg_lo:[0,1] neg_hi:[0,1]
	v_pk_add_f32 v[132:133], v[132:133], v[14:15] op_sel_hi:[1,0] neg_lo:[0,1] neg_hi:[0,1]
	v_pk_add_f32 v[150:151], v[150:151], v[14:15] op_sel_hi:[1,0] neg_lo:[0,1] neg_hi:[0,1]
	v_pk_add_f32 v[134:135], v[134:135], v[14:15] op_sel_hi:[1,0] neg_lo:[0,1] neg_hi:[0,1]
	v_exp_f32_e64 v14, -v14
	v_mov_b32_e32 v49, v48
	v_mov_b32_e32 v50, v48
	v_mov_b32_e32 v51, v48
	v_mov_b32_e32 v52, v48
	v_mov_b32_e32 v53, v48
	v_mov_b32_e32 v54, v48
	v_mov_b32_e32 v55, v48
	v_mov_b32_e32 v56, v48
	v_mov_b32_e32 v57, v48
	v_mov_b32_e32 v58, v48
	v_mov_b32_e32 v59, v48
	v_mov_b32_e32 v60, v48
	v_mov_b32_e32 v61, v48
	v_mov_b32_e32 v62, v48
	v_mov_b32_e32 v63, v48
	s_nop 11
	v_pk_mul_f32 v[30:31], v[30:31], v[14:15] op_sel_hi:[1,0]
	v_pk_mul_f32 v[28:29], v[28:29], v[14:15] op_sel_hi:[1,0]
	v_pk_mul_f32 v[26:27], v[26:27], v[14:15] op_sel_hi:[1,0]
	v_pk_mul_f32 v[24:25], v[24:25], v[14:15] op_sel_hi:[1,0]
	v_pk_mul_f32 v[22:23], v[22:23], v[14:15] op_sel_hi:[1,0]
	v_pk_mul_f32 v[20:21], v[20:21], v[14:15] op_sel_hi:[1,0]
	v_pk_mul_f32 v[18:19], v[18:19], v[14:15] op_sel_hi:[1,0]
	v_pk_mul_f32 v[16:17], v[16:17], v[14:15] op_sel_hi:[1,0]
	v_pk_mul_f32 v[46:47], v[46:47], v[14:15] op_sel_hi:[1,0]
	v_pk_mul_f32 v[44:45], v[44:45], v[14:15] op_sel_hi:[1,0]
	v_pk_mul_f32 v[42:43], v[42:43], v[14:15] op_sel_hi:[1,0]
	v_pk_mul_f32 v[40:41], v[40:41], v[14:15] op_sel_hi:[1,0]
	v_pk_mul_f32 v[38:39], v[38:39], v[14:15] op_sel_hi:[1,0]
	v_pk_mul_f32 v[36:37], v[36:37], v[14:15] op_sel_hi:[1,0]
	v_pk_mul_f32 v[34:35], v[34:35], v[14:15] op_sel_hi:[1,0]
	v_pk_mul_f32 v[32:33], v[32:33], v[14:15] op_sel_hi:[1,0]
	v_mul_f32_e32 v64, v64, v14
